# GEMM loops: LDS-DMA via SGPR base + 32-bit VGPR offset (no VALU address adds), precomputed LDS read addresses; P4 attention K/V LDS fragment prefetch; pipelined residual epilogue
# speedup vs baseline: 1.0088x; 1.0088x over previous
.LBB0_191:
	s_ashr_i32 s9, s8, 31
	s_lshl_b64 s[10:11], s[8:9], 20
	s_add_u32 s10, s66, s10
	s_addc_u32 s11, s67, s11
	s_and_b64 s[12:13], s[0:1], exec
	s_cselect_b32 s9, s11, s15
	s_cselect_b32 s30, s10, s14
	s_ashr_i32 s7, s6, 31
	s_lshl_b64 s[12:13], s[6:7], 20
	s_add_u32 s12, s50, s12
	s_addc_u32 s13, s51, s13
	s_and_b64 s[18:19], s[0:1], exec
	s_cselect_b32 s7, s13, s17
	s_cselect_b32 s31, s12, s16
	s_add_u32 s33, s16, 0x100
	s_addc_u32 s34, s17, 0
	s_add_u32 s14, s14, 0x80080
	v_mov_b32_e32 v0, 0
	s_addc_u32 s15, s15, 0
	s_mov_b32 s35, -2
	v_mov_b32_e32 v1, v0
	v_mov_b32_e32 v2, v0
	v_mov_b32_e32 v3, v0
	v_mov_b32_e32 v4, v0
	v_mov_b32_e32 v5, v0
	v_mov_b32_e32 v6, v0
	v_mov_b32_e32 v7, v0
	v_mov_b32_e32 v8, v0
	v_mov_b32_e32 v9, v0
	v_mov_b32_e32 v10, v0
	v_mov_b32_e32 v11, v0
	v_mov_b32_e32 v16, v0
	v_mov_b32_e32 v17, v0
	v_mov_b32_e32 v18, v0
	v_mov_b32_e32 v19, v0
	v_mov_b32_e32 v24, v0
	v_mov_b32_e32 v25, v0
	v_mov_b32_e32 v26, v0
	v_mov_b32_e32 v27, v0
	v_mov_b32_e32 v32, v0
	v_mov_b32_e32 v33, v0
	v_mov_b32_e32 v34, v0
	v_mov_b32_e32 v35, v0
	v_mov_b32_e32 v40, v0
	v_mov_b32_e32 v41, v0
	v_mov_b32_e32 v42, v0
	v_mov_b32_e32 v43, v0
	v_mov_b32_e32 v48, v0
	v_mov_b32_e32 v49, v0
	v_mov_b32_e32 v50, v0
	v_mov_b32_e32 v51, v0
	v_mov_b32_e32 v12, v0
	v_mov_b32_e32 v13, v0
	v_mov_b32_e32 v14, v0
	v_mov_b32_e32 v15, v0
	v_mov_b32_e32 v20, v0
	v_mov_b32_e32 v21, v0
	v_mov_b32_e32 v22, v0
	v_mov_b32_e32 v23, v0
	v_mov_b32_e32 v28, v0
	v_mov_b32_e32 v29, v0
	v_mov_b32_e32 v30, v0
	v_mov_b32_e32 v31, v0
	v_mov_b32_e32 v36, v0
	v_mov_b32_e32 v37, v0
	v_mov_b32_e32 v38, v0
	v_mov_b32_e32 v39, v0
	v_mov_b32_e32 v44, v0
	v_mov_b32_e32 v45, v0
	v_mov_b32_e32 v46, v0
	v_mov_b32_e32 v47, v0
	v_mov_b32_e32 v52, v0
	v_mov_b32_e32 v53, v0
	v_mov_b32_e32 v54, v0
	v_mov_b32_e32 v55, v0
	v_mov_b32_e32 v56, v0
	v_mov_b32_e32 v57, v0
	v_mov_b32_e32 v58, v0
	v_mov_b32_e32 v59, v0
	v_mov_b32_e32 v60, v0
	v_mov_b32_e32 v61, v0
	v_mov_b32_e32 v62, v0
	v_mov_b32_e32 v63, v0
	v_mov_b32_e32 v64, v0
	v_mov_b32_e32 v65, v0
	v_mov_b32_e32 v66, v0
	v_mov_b32_e32 v67, v0
	v_mov_b32_e32 v68, v0
	v_mov_b32_e32 v69, v0
	v_mov_b32_e32 v70, v0
	v_mov_b32_e32 v71, v0
	v_mov_b32_e32 v72, v0
	v_mov_b32_e32 v73, v0
	v_mov_b32_e32 v74, v0
	v_mov_b32_e32 v75, v0
	v_mov_b32_e32 v80, v0
	v_mov_b32_e32 v81, v0
	v_mov_b32_e32 v82, v0
	v_mov_b32_e32 v83, v0
	v_mov_b32_e32 v88, v0
	v_mov_b32_e32 v89, v0
	v_mov_b32_e32 v90, v0
	v_mov_b32_e32 v91, v0
	v_mov_b32_e32 v96, v0
	v_mov_b32_e32 v97, v0
	v_mov_b32_e32 v98, v0
	v_mov_b32_e32 v99, v0
	v_mov_b32_e32 v104, v0
	v_mov_b32_e32 v105, v0
	v_mov_b32_e32 v106, v0
	v_mov_b32_e32 v107, v0
	v_mov_b32_e32 v112, v0
	v_mov_b32_e32 v113, v0
	v_mov_b32_e32 v114, v0
	v_mov_b32_e32 v115, v0
	v_mov_b32_e32 v76, v0
	v_mov_b32_e32 v77, v0
	v_mov_b32_e32 v78, v0
	v_mov_b32_e32 v79, v0
	v_mov_b32_e32 v84, v0
	v_mov_b32_e32 v85, v0
	v_mov_b32_e32 v86, v0
	v_mov_b32_e32 v87, v0
	v_mov_b32_e32 v92, v0
	v_mov_b32_e32 v93, v0
	v_mov_b32_e32 v94, v0
	v_mov_b32_e32 v95, v0
	v_mov_b32_e32 v100, v0
	v_mov_b32_e32 v101, v0
	v_mov_b32_e32 v102, v0
	v_mov_b32_e32 v103, v0
	v_mov_b32_e32 v108, v0
	v_mov_b32_e32 v109, v0
	v_mov_b32_e32 v110, v0
	v_mov_b32_e32 v111, v0
	v_mov_b32_e32 v116, v0
	v_mov_b32_e32 v117, v0
	v_mov_b32_e32 v118, v0
	v_mov_b32_e32 v119, v0
	v_mov_b32_e32 v120, v0
	v_mov_b32_e32 v121, v0
	v_mov_b32_e32 v122, v0
	v_mov_b32_e32 v123, v0
	v_mov_b32_e32 v124, v0
	v_mov_b32_e32 v125, v0
	v_mov_b32_e32 v126, v0
	v_mov_b32_e32 v127, v0
	s_mov_b64 s[74:75], 0x80
	v_add_u32_e32 v234, 0x10000, v143
	v_add_u32_e32 v235, 0x14000, v143
	v_add_u32_e32 v236, 0x18000, v143
	v_add_u32_e32 v237, 0x1c000, v143
.LBB0_192:
	s_add_u32 s16, s14, 0xfff80080
	s_addc_u32 s17, s15, -1
	s_add_i32 s36, 0, 0x10000
	s_cmp_eq_u32 s35, 28
	s_cselect_b32 s19, s9, s17
	s_cselect_b32 s18, s30, s16
	s_cselect_b32 s17, s7, s34
	s_cselect_b32 s16, s31, s33
	s_add_i32 s38, 0, 0x14000
	ds_read_b128 v[138:141], v234
	ds_read_b128 v[146:149], v234 offset:1024
	ds_read_b128 v[162:165], v234 offset:2048
	ds_read_b128 v[166:169], v234 offset:3072
	ds_read_b128 v[170:173], v235
	ds_read_b128 v[174:177], v235 offset:1024
	ds_read_b128 v[178:181], v235 offset:2048
	ds_read_b128 v[182:185], v235 offset:3072
	s_add_i32 m0, s21, 0xc000
	ds_read_b128 v[186:189], v145
	ds_read_b128 v[190:193], v145 offset:1024
	ds_read_b128 v[194:197], v145 offset:2048
	ds_read_b128 v[198:201], v145 offset:3072
	ds_read_b128 v[202:205], v145 offset:4096
	ds_read_b128 v[214:217], v145 offset:5120
	ds_read_b128 v[218:221], v145 offset:6144
	ds_read_b128 v[222:225], v145 offset:7168
	global_load_lds_dwordx4 v136, s[14:15]
	s_add_i32 m0, s21, 0xe000
	s_nop 0
	global_load_lds_dwordx4 v134, s[14:15]
	s_waitcnt vmcnt(8)
	s_waitcnt lgkmcnt(0)
	s_barrier
	s_setprio 1
	s_waitcnt lgkmcnt(0)
	v_mfma_f32_16x16x32_bf16 v[124:127], v[138:141], v[186:189], v[124:127]
	v_mfma_f32_16x16x32_bf16 v[120:123], v[162:165], v[186:189], v[120:123]
	v_mfma_f32_16x16x32_bf16 v[116:119], v[138:141], v[194:197], v[116:119]
	v_mfma_f32_16x16x32_bf16 v[108:111], v[162:165], v[194:197], v[108:111]
	v_mfma_f32_16x16x32_bf16 v[100:103], v[138:141], v[202:205], v[100:103]
	v_mfma_f32_16x16x32_bf16 v[92:95], v[162:165], v[202:205], v[92:95]
	v_mfma_f32_16x16x32_bf16 v[84:87], v[138:141], v[218:221], v[84:87]
	v_mfma_f32_16x16x32_bf16 v[76:79], v[162:165], v[218:221], v[76:79]
	v_mfma_f32_16x16x32_bf16 v[124:127], v[146:149], v[190:193], v[124:127]
	v_mfma_f32_16x16x32_bf16 v[120:123], v[166:169], v[190:193], v[120:123]
	v_mfma_f32_16x16x32_bf16 v[116:119], v[146:149], v[198:201], v[116:119]
	v_mfma_f32_16x16x32_bf16 v[108:111], v[166:169], v[198:201], v[108:111]
	v_mfma_f32_16x16x32_bf16 v[100:103], v[146:149], v[214:217], v[100:103]
	v_mfma_f32_16x16x32_bf16 v[92:95], v[166:169], v[214:217], v[92:95]
	v_mfma_f32_16x16x32_bf16 v[84:87], v[146:149], v[222:225], v[84:87]
	v_mfma_f32_16x16x32_bf16 v[76:79], v[166:169], v[222:225], v[76:79]
	s_setprio 0
	s_setprio 1
	v_mfma_f32_16x16x32_bf16 v[112:115], v[170:173], v[186:189], v[112:115]
	v_mfma_f32_16x16x32_bf16 v[104:107], v[178:181], v[186:189], v[104:107]
	v_mfma_f32_16x16x32_bf16 v[96:99], v[170:173], v[194:197], v[96:99]
	v_mfma_f32_16x16x32_bf16 v[88:91], v[178:181], v[194:197], v[88:91]
	v_mfma_f32_16x16x32_bf16 v[80:83], v[170:173], v[202:205], v[80:83]
	v_mfma_f32_16x16x32_bf16 v[72:75], v[178:181], v[202:205], v[72:75]
	v_mfma_f32_16x16x32_bf16 v[68:71], v[170:173], v[218:221], v[68:71]
	v_mfma_f32_16x16x32_bf16 v[64:67], v[178:181], v[218:221], v[64:67]
	v_mfma_f32_16x16x32_bf16 v[112:115], v[174:177], v[190:193], v[112:115]
	v_mfma_f32_16x16x32_bf16 v[104:107], v[182:185], v[190:193], v[104:107]
	v_mfma_f32_16x16x32_bf16 v[96:99], v[174:177], v[198:201], v[96:99]
	v_mfma_f32_16x16x32_bf16 v[88:91], v[182:185], v[198:201], v[88:91]
	v_mfma_f32_16x16x32_bf16 v[80:83], v[174:177], v[214:217], v[80:83]
	v_mfma_f32_16x16x32_bf16 v[72:75], v[182:185], v[214:217], v[72:75]
	v_mfma_f32_16x16x32_bf16 v[68:71], v[174:177], v[222:225], v[68:71]
	v_mfma_f32_16x16x32_bf16 v[64:67], v[182:185], v[222:225], v[64:67]
	s_setprio 0
	s_barrier
	s_add_i32 s36, s36, s20
	s_add_u32 s100, s16, 0x80
	s_addc_u32 s101, s17, 0
	s_mov_b32 m0, s36
	ds_read_b128 v[186:189], v145 offset:16384
	ds_read_b128 v[190:193], v145 offset:17408
	ds_read_b128 v[194:197], v145 offset:18432
	ds_read_b128 v[198:201], v145 offset:19456
	ds_read_b128 v[202:205], v145 offset:20480
	ds_read_b128 v[214:217], v145 offset:21504
	ds_read_b128 v[218:221], v145 offset:22528
	ds_read_b128 v[222:225], v145 offset:23552
	global_load_lds_dwordx4 v152, s[16:17]
	s_add_i32 m0, s36, 0x2000
	s_add_u32 s36, s16, 0x80000
	s_addc_u32 s37, s17, 0
	s_add_i32 s38, s38, s20
	global_load_lds_dwordx4 v128, s[16:17]
	s_mov_b32 m0, s38
	s_nop 0
	global_load_lds_dwordx4 v152, s[36:37]
	s_add_i32 m0, s38, 0x2000
	s_nop 0
	global_load_lds_dwordx4 v128, s[36:37]
	s_add_u32 s98, s18, 0x80
	s_addc_u32 s99, s19, 0
	s_mov_b32 m0, s21
	s_nop 0
	global_load_lds_dwordx4 v132, s[18:19]
	s_mov_b32 m0, s22
	s_nop 0
	global_load_lds_dwordx4 v130, s[18:19]
	s_waitcnt vmcnt(8)
	s_waitcnt lgkmcnt(0)
	s_barrier
	s_setprio 1
	s_waitcnt lgkmcnt(0)
	v_mfma_f32_16x16x32_bf16 v[60:63], v[138:141], v[186:189], v[60:63]
	v_mfma_f32_16x16x32_bf16 v[56:59], v[162:165], v[186:189], v[56:59]
	v_mfma_f32_16x16x32_bf16 v[52:55], v[138:141], v[194:197], v[52:55]
	v_mfma_f32_16x16x32_bf16 v[44:47], v[162:165], v[194:197], v[44:47]
	v_mfma_f32_16x16x32_bf16 v[36:39], v[138:141], v[202:205], v[36:39]
	v_mfma_f32_16x16x32_bf16 v[28:31], v[162:165], v[202:205], v[28:31]
	v_mfma_f32_16x16x32_bf16 v[20:23], v[138:141], v[218:221], v[20:23]
	v_mfma_f32_16x16x32_bf16 v[12:15], v[162:165], v[218:221], v[12:15]
	v_mfma_f32_16x16x32_bf16 v[60:63], v[146:149], v[190:193], v[60:63]
	v_mfma_f32_16x16x32_bf16 v[56:59], v[166:169], v[190:193], v[56:59]
	v_mfma_f32_16x16x32_bf16 v[52:55], v[146:149], v[198:201], v[52:55]
	v_mfma_f32_16x16x32_bf16 v[44:47], v[166:169], v[198:201], v[44:47]
	v_mfma_f32_16x16x32_bf16 v[36:39], v[146:149], v[214:217], v[36:39]
	v_mfma_f32_16x16x32_bf16 v[28:31], v[166:169], v[214:217], v[28:31]
	v_mfma_f32_16x16x32_bf16 v[20:23], v[146:149], v[222:225], v[20:23]
	v_mfma_f32_16x16x32_bf16 v[12:15], v[166:169], v[222:225], v[12:15]
	s_setprio 0
	s_setprio 1
	v_mfma_f32_16x16x32_bf16 v[48:51], v[170:173], v[186:189], v[48:51]
	v_mfma_f32_16x16x32_bf16 v[40:43], v[178:181], v[186:189], v[40:43]
	v_mfma_f32_16x16x32_bf16 v[32:35], v[170:173], v[194:197], v[32:35]
	v_mfma_f32_16x16x32_bf16 v[24:27], v[178:181], v[194:197], v[24:27]
	v_mfma_f32_16x16x32_bf16 v[16:19], v[170:173], v[202:205], v[16:19]
	v_mfma_f32_16x16x32_bf16 v[8:11], v[178:181], v[202:205], v[8:11]
	v_mfma_f32_16x16x32_bf16 v[4:7], v[170:173], v[218:221], v[4:7]
	v_mfma_f32_16x16x32_bf16 v[0:3], v[178:181], v[218:221], v[0:3]
	v_mfma_f32_16x16x32_bf16 v[48:51], v[174:177], v[190:193], v[48:51]
	v_mfma_f32_16x16x32_bf16 v[40:43], v[182:185], v[190:193], v[40:43]
	v_mfma_f32_16x16x32_bf16 v[32:35], v[174:177], v[198:201], v[32:35]
	v_mfma_f32_16x16x32_bf16 v[24:27], v[182:185], v[198:201], v[24:27]
	v_mfma_f32_16x16x32_bf16 v[16:19], v[174:177], v[214:217], v[16:19]
	v_mfma_f32_16x16x32_bf16 v[8:11], v[182:185], v[214:217], v[8:11]
	v_mfma_f32_16x16x32_bf16 v[4:7], v[174:177], v[222:225], v[4:7]
	v_mfma_f32_16x16x32_bf16 v[0:3], v[182:185], v[222:225], v[0:3]
	s_setprio 0
	s_barrier
	s_add_i32 s36, 0, 0x18000
	s_add_i32 s37, 0, 0x1c000
	ds_read_b128 v[138:141], v236
	ds_read_b128 v[146:149], v236 offset:1024
	ds_read_b128 v[162:165], v236 offset:2048
	ds_read_b128 v[166:169], v236 offset:3072
	ds_read_b128 v[170:173], v237
	ds_read_b128 v[174:177], v237 offset:1024
	ds_read_b128 v[178:181], v237 offset:2048
	ds_read_b128 v[182:185], v237 offset:3072
	s_add_u32 s18, s18, 0x80000
	s_addc_u32 s19, s19, 0
	s_mov_b32 m0, s23
	ds_read_b128 v[186:189], v145 offset:32768
	ds_read_b128 v[190:193], v145 offset:33792
	ds_read_b128 v[194:197], v145 offset:34816
	ds_read_b128 v[198:201], v145 offset:35840
	ds_read_b128 v[202:205], v145 offset:36864
	ds_read_b128 v[214:217], v145 offset:37888
	ds_read_b128 v[218:221], v145 offset:38912
	ds_read_b128 v[222:225], v145 offset:39936
	global_load_lds_dwordx4 v132, s[18:19]
	s_mov_b32 m0, s24
	s_nop 0
	global_load_lds_dwordx4 v130, s[18:19]
	s_waitcnt vmcnt(8)
	s_waitcnt lgkmcnt(0)
	s_barrier
	s_setprio 1
	s_waitcnt lgkmcnt(0)
	v_mfma_f32_16x16x32_bf16 v[124:127], v[138:141], v[186:189], v[124:127]
	v_mfma_f32_16x16x32_bf16 v[120:123], v[162:165], v[186:189], v[120:123]
	v_mfma_f32_16x16x32_bf16 v[116:119], v[138:141], v[194:197], v[116:119]
	v_mfma_f32_16x16x32_bf16 v[108:111], v[162:165], v[194:197], v[108:111]
	v_mfma_f32_16x16x32_bf16 v[100:103], v[138:141], v[202:205], v[100:103]
	v_mfma_f32_16x16x32_bf16 v[92:95], v[162:165], v[202:205], v[92:95]
	v_mfma_f32_16x16x32_bf16 v[84:87], v[138:141], v[218:221], v[84:87]
	v_mfma_f32_16x16x32_bf16 v[76:79], v[162:165], v[218:221], v[76:79]
	v_mfma_f32_16x16x32_bf16 v[124:127], v[146:149], v[190:193], v[124:127]
	v_mfma_f32_16x16x32_bf16 v[120:123], v[166:169], v[190:193], v[120:123]
	v_mfma_f32_16x16x32_bf16 v[116:119], v[146:149], v[198:201], v[116:119]
	v_mfma_f32_16x16x32_bf16 v[108:111], v[166:169], v[198:201], v[108:111]
	v_mfma_f32_16x16x32_bf16 v[100:103], v[146:149], v[214:217], v[100:103]
	v_mfma_f32_16x16x32_bf16 v[92:95], v[166:169], v[214:217], v[92:95]
	v_mfma_f32_16x16x32_bf16 v[84:87], v[146:149], v[222:225], v[84:87]
	v_mfma_f32_16x16x32_bf16 v[76:79], v[166:169], v[222:225], v[76:79]
	s_setprio 0
	s_setprio 1
	v_mfma_f32_16x16x32_bf16 v[112:115], v[170:173], v[186:189], v[112:115]
	v_mfma_f32_16x16x32_bf16 v[104:107], v[178:181], v[186:189], v[104:107]
	v_mfma_f32_16x16x32_bf16 v[96:99], v[170:173], v[194:197], v[96:99]
	v_mfma_f32_16x16x32_bf16 v[88:91], v[178:181], v[194:197], v[88:91]
	v_mfma_f32_16x16x32_bf16 v[80:83], v[170:173], v[202:205], v[80:83]
	v_mfma_f32_16x16x32_bf16 v[72:75], v[178:181], v[202:205], v[72:75]
	v_mfma_f32_16x16x32_bf16 v[68:71], v[170:173], v[218:221], v[68:71]
	v_mfma_f32_16x16x32_bf16 v[64:67], v[178:181], v[218:221], v[64:67]
	v_mfma_f32_16x16x32_bf16 v[112:115], v[174:177], v[190:193], v[112:115]
	v_mfma_f32_16x16x32_bf16 v[104:107], v[182:185], v[190:193], v[104:107]
	v_mfma_f32_16x16x32_bf16 v[96:99], v[174:177], v[198:201], v[96:99]
	v_mfma_f32_16x16x32_bf16 v[88:91], v[182:185], v[198:201], v[88:91]
	v_mfma_f32_16x16x32_bf16 v[80:83], v[174:177], v[214:217], v[80:83]
	v_mfma_f32_16x16x32_bf16 v[72:75], v[182:185], v[214:217], v[72:75]
	v_mfma_f32_16x16x32_bf16 v[68:71], v[174:177], v[222:225], v[68:71]
	v_mfma_f32_16x16x32_bf16 v[64:67], v[182:185], v[222:225], v[64:67]
	s_setprio 0
	s_barrier
	s_add_i32 s18, s36, s20
	s_mov_b32 m0, s18
	ds_read_b128 v[186:189], v145 offset:49152
	ds_read_b128 v[190:193], v145 offset:50176
	ds_read_b128 v[194:197], v145 offset:51200
	ds_read_b128 v[198:201], v145 offset:52224
	ds_read_b128 v[202:205], v145 offset:53248
	ds_read_b128 v[214:217], v145 offset:54272
	ds_read_b128 v[218:221], v145 offset:55296
	ds_read_b128 v[222:225], v145 offset:56320
	global_load_lds_dwordx4 v152, s[100:101]
	s_add_i32 m0, s18, 0x2000
	s_add_u32 s16, s16, 0x80080
	s_addc_u32 s17, s17, 0
	s_add_i32 s18, s37, s20
	global_load_lds_dwordx4 v128, s[100:101]
	s_mov_b32 m0, s18
	s_nop 0
	global_load_lds_dwordx4 v152, s[16:17]
	s_add_i32 m0, s18, 0x2000
	s_nop 0
	global_load_lds_dwordx4 v128, s[16:17]
	s_mov_b32 m0, s25
	s_nop 0
	global_load_lds_dwordx4 v132, s[98:99]
	s_mov_b32 m0, s26
	s_nop 0
	global_load_lds_dwordx4 v130, s[98:99]
	s_waitcnt vmcnt(8)
	s_waitcnt lgkmcnt(0)
	s_barrier
	s_setprio 1
	s_waitcnt lgkmcnt(0)
	v_mfma_f32_16x16x32_bf16 v[60:63], v[138:141], v[186:189], v[60:63]
	v_mfma_f32_16x16x32_bf16 v[56:59], v[162:165], v[186:189], v[56:59]
	v_mfma_f32_16x16x32_bf16 v[52:55], v[138:141], v[194:197], v[52:55]
	v_mfma_f32_16x16x32_bf16 v[44:47], v[162:165], v[194:197], v[44:47]
	v_mfma_f32_16x16x32_bf16 v[36:39], v[138:141], v[202:205], v[36:39]
	v_mfma_f32_16x16x32_bf16 v[28:31], v[162:165], v[202:205], v[28:31]
	v_mfma_f32_16x16x32_bf16 v[20:23], v[138:141], v[218:221], v[20:23]
	v_mfma_f32_16x16x32_bf16 v[12:15], v[162:165], v[218:221], v[12:15]
	v_mfma_f32_16x16x32_bf16 v[60:63], v[146:149], v[190:193], v[60:63]
	v_mfma_f32_16x16x32_bf16 v[56:59], v[166:169], v[190:193], v[56:59]
	v_mfma_f32_16x16x32_bf16 v[52:55], v[146:149], v[198:201], v[52:55]
	v_mfma_f32_16x16x32_bf16 v[44:47], v[166:169], v[198:201], v[44:47]
	v_mfma_f32_16x16x32_bf16 v[36:39], v[146:149], v[214:217], v[36:39]
	v_mfma_f32_16x16x32_bf16 v[28:31], v[166:169], v[214:217], v[28:31]
	v_mfma_f32_16x16x32_bf16 v[20:23], v[146:149], v[222:225], v[20:23]
	v_mfma_f32_16x16x32_bf16 v[12:15], v[166:169], v[222:225], v[12:15]
	s_setprio 0
	s_setprio 1
	v_mfma_f32_16x16x32_bf16 v[48:51], v[170:173], v[186:189], v[48:51]
	v_mfma_f32_16x16x32_bf16 v[40:43], v[178:181], v[186:189], v[40:43]
	v_mfma_f32_16x16x32_bf16 v[32:35], v[170:173], v[194:197], v[32:35]
	v_mfma_f32_16x16x32_bf16 v[24:27], v[178:181], v[194:197], v[24:27]
	v_mfma_f32_16x16x32_bf16 v[16:19], v[170:173], v[202:205], v[16:19]
	v_mfma_f32_16x16x32_bf16 v[8:11], v[178:181], v[202:205], v[8:11]
	v_mfma_f32_16x16x32_bf16 v[4:7], v[170:173], v[218:221], v[4:7]
	v_mfma_f32_16x16x32_bf16 v[0:3], v[178:181], v[218:221], v[0:3]
	v_mfma_f32_16x16x32_bf16 v[48:51], v[174:177], v[190:193], v[48:51]
	v_mfma_f32_16x16x32_bf16 v[40:43], v[182:185], v[190:193], v[40:43]
	v_mfma_f32_16x16x32_bf16 v[32:35], v[174:177], v[198:201], v[32:35]
	v_mfma_f32_16x16x32_bf16 v[24:27], v[182:185], v[198:201], v[24:27]
	v_mfma_f32_16x16x32_bf16 v[16:19], v[174:177], v[214:217], v[16:19]
	v_mfma_f32_16x16x32_bf16 v[8:11], v[182:185], v[214:217], v[8:11]
	v_mfma_f32_16x16x32_bf16 v[4:7], v[174:177], v[222:225], v[4:7]
	v_mfma_f32_16x16x32_bf16 v[0:3], v[182:185], v[222:225], v[0:3]
	s_setprio 0
	s_barrier
	s_add_i32 s35, s35, 2
	s_add_u32 s33, s33, 0x100
	s_addc_u32 s34, s34, 0
	s_add_u32 s14, s14, 0x100
	s_addc_u32 s15, s15, 0
	s_cmp_gt_u32 s35, 29
	s_cbranch_scc0 .LBB0_192
	s_and_b64 vcc, exec, s[4:5]
	s_cbranch_vccz .LBB0_195
	s_barrier

.LBB0_1174:
	s_and_b32 s12, s23, 0x1000
	v_lshl_add_u32 v155, s12, 1, v152
	ds_read_b128 v[80:83], v155
	ds_read_b128 v[84:87], v155 offset:1024
	ds_read_b128 v[88:91], v155 offset:2048
	ds_read_b128 v[92:95], v155 offset:3072
	ds_read_b128 v[96:99], v155 offset:4096
	ds_read_b128 v[100:103], v155 offset:5120
	ds_read_b128 v[104:107], v155 offset:6144
	ds_read_b128 v[108:111], v155 offset:7168
	s_mov_b64 s[12:13], -1
	s_and_b64 vcc, s[2:3], exec
	s_waitcnt lgkmcnt(7)
	v_mfma_f32_32x32x16_bf16 v[64:79], v[80:83], v[112:115], 0
	s_waitcnt lgkmcnt(6)
	v_mfma_f32_32x32x16_bf16 v[64:79], v[84:87], v[116:119], v[64:79]
	s_waitcnt lgkmcnt(5)
	v_mfma_f32_32x32x16_bf16 v[64:79], v[88:91], v[120:123], v[64:79]
	s_waitcnt lgkmcnt(4)
	v_mfma_f32_32x32x16_bf16 v[64:79], v[92:95], v[124:127], v[64:79]
	s_waitcnt lgkmcnt(3)
	v_mfma_f32_32x32x16_bf16 v[64:79], v[96:99], v[128:131], v[64:79]
	s_waitcnt lgkmcnt(2)
	v_mfma_f32_32x32x16_bf16 v[64:79], v[100:103], v[132:135], v[64:79]
	s_waitcnt lgkmcnt(1)
	v_mfma_f32_32x32x16_bf16 v[64:79], v[104:107], v[136:139], v[64:79]
	s_waitcnt lgkmcnt(0)
	v_mfma_f32_32x32x16_bf16 v[64:79], v[108:111], v[140:143], v[64:79]
	ds_read_b128 v[234:237], v155 offset:16384
	ds_read_b128 v[238:241], v155 offset:17408
	ds_read_b128 v[242:245], v155 offset:18432
	ds_read_b128 v[246:249], v155 offset:19456
	s_cbranch_vccz .LBB0_1180
	s_sub_i32 s2, s27, s40
	s_cmpk_lt_i32 s2, 0x9f
	s_mov_b64 s[2:3], -1
	s_cbranch_scc1 .LBB0_1177
	s_mov_b32 s2, 0x3fb8aa3b
	v_add_u32_e32 v111, s40, v166
	s_nop 4
	v_pk_fma_f32 v[94:95], v[78:79], s[2:3], v[188:189] op_sel_hi:[1,0,1]
	v_pk_fma_f32 v[92:93], v[76:77], s[2:3], v[186:187] op_sel_hi:[1,0,1]
	v_pk_fma_f32 v[90:91], v[74:75], s[2:3], v[184:185] op_sel_hi:[1,0,1]
	v_pk_fma_f32 v[88:89], v[72:73], s[2:3], v[182:183] op_sel_hi:[1,0,1]
	v_pk_fma_f32 v[86:87], v[70:71], s[2:3], v[180:181] op_sel_hi:[1,0,1]
	v_pk_fma_f32 v[84:85], v[68:69], s[2:3], v[178:179] op_sel_hi:[1,0,1]
	v_pk_fma_f32 v[82:83], v[66:67], s[2:3], v[176:177] op_sel_hi:[1,0,1]
	v_pk_fma_f32 v[80:81], v[64:65], s[2:3], v[172:173] op_sel_hi:[1,0,1]
	v_sub_u32_e32 v96, v162, v111
	v_xad_u32 v97, v111, -1, v162
	v_sub_u32_e32 v98, v220, v111
	v_sub_u32_e32 v99, v221, v111
	v_sub_u32_e32 v100, v222, v111
	v_sub_u32_e32 v101, v223, v111
	v_sub_u32_e32 v102, v224, v111
	v_sub_u32_e32 v103, v225, v111
	v_sub_u32_e32 v104, v226, v111
	v_sub_u32_e32 v105, v227, v111
	v_sub_u32_e32 v106, v228, v111
	v_sub_u32_e32 v107, v229, v111
	v_sub_u32_e32 v108, v230, v111
	v_sub_u32_e32 v109, v231, v111
	v_sub_u32_e32 v110, v232, v111
	v_sub_u32_e32 v111, v233, v111
	s_mov_b64 s[2:3], 0

.LBB0_1186:
	s_nop 8
	v_exp_f32_e32 v67, v95
	v_cvt_pk_bf16_f32 v64, v96, v97
	v_cvt_pk_bf16_f32 v65, v98, v99
	v_cvt_pk_bf16_f32 v66, v100, v101
	s_nop 0
	v_cndmask_b32_e64 v80, 0, v67, s[2:3]
	v_cvt_pk_bf16_f32 v67, v102, v103
	v_cvt_pk_bf16_f32 v68, v104, v105
	v_cvt_pk_bf16_f32 v69, v106, v107
	v_cvt_pk_bf16_f32 v70, v108, v109
	v_cvt_pk_bf16_f32 v71, v110, v80
	ds_read_b128 v[72:75], v155 offset:20480
	ds_read_b128 v[76:79], v155 offset:21504
	ds_read_b128 v[84:87], v155 offset:22528
	ds_read_b128 v[88:91], v155 offset:23552
	s_waitcnt lgkmcnt(4)
	v_mfma_f32_32x32x16_bf16 v[48:63], v[64:67], v[234:237], v[48:63]
	v_mfma_f32_32x32x16_bf16 v[32:47], v[64:67], v[242:245], v[32:47]
	v_mfma_f32_32x32x16_bf16 v[48:63], v[68:71], v[238:241], v[48:63]
	v_mfma_f32_32x32x16_bf16 v[32:47], v[68:71], v[246:249], v[32:47]
	s_waitcnt lgkmcnt(2)
	v_mfma_f32_32x32x16_bf16 v[16:31], v[64:67], v[72:75], v[16:31]
	s_waitcnt lgkmcnt(1)
	v_mfma_f32_32x32x16_bf16 v[0:15], v[64:67], v[84:87], v[0:15]
	v_add_f32_e32 v64, v80, v204
	v_add_f32_e32 v205, v205, v64
	v_mfma_f32_32x32x16_bf16 v[16:31], v[68:71], v[76:79], v[16:31]
	s_waitcnt lgkmcnt(0)
	v_mfma_f32_32x32x16_bf16 v[0:15], v[68:71], v[88:91], v[0:15]
	s_cmp_lg_u32 s18, s39
	s_cbranch_scc1 .LBB0_1172

.LBB0_1382:
	s_ashr_i32 s9, s8, 31
	s_lshl_b64 s[10:11], s[8:9], 20
	s_add_u32 s10, s66, s10
	s_addc_u32 s11, s67, s11
	s_and_b64 s[12:13], s[0:1], exec
	s_cselect_b32 s9, s11, s15
	s_cselect_b32 s33, s10, s14
	s_ashr_i32 s7, s6, 31
	s_lshl_b64 s[12:13], s[6:7], 20
	s_add_u32 s12, s60, s12
	s_addc_u32 s13, s61, s13
	s_and_b64 s[18:19], s[0:1], exec
	s_cselect_b32 s7, s13, s17
	s_cselect_b32 s34, s12, s16
	s_add_u32 s35, s16, 0x100
	v_mov_b32_e32 v0, 0
	s_addc_u32 s36, s17, 0
	s_mov_b32 s37, -2
	v_mov_b32_e32 v1, v0
	v_mov_b32_e32 v2, v0
	v_mov_b32_e32 v3, v0
	v_mov_b32_e32 v4, v0
	v_mov_b32_e32 v5, v0
	v_mov_b32_e32 v6, v0
	v_mov_b32_e32 v7, v0
	v_mov_b32_e32 v16, v0
	v_mov_b32_e32 v17, v0
	v_mov_b32_e32 v18, v0
	v_mov_b32_e32 v19, v0
	v_mov_b32_e32 v20, v0
	v_mov_b32_e32 v21, v0
	v_mov_b32_e32 v22, v0
	v_mov_b32_e32 v23, v0
	v_mov_b32_e32 v32, v0
	v_mov_b32_e32 v33, v0
	v_mov_b32_e32 v34, v0
	v_mov_b32_e32 v35, v0
	v_mov_b32_e32 v36, v0
	v_mov_b32_e32 v37, v0
	v_mov_b32_e32 v38, v0
	v_mov_b32_e32 v39, v0
	v_mov_b32_e32 v48, v0
	v_mov_b32_e32 v49, v0
	v_mov_b32_e32 v50, v0
	v_mov_b32_e32 v51, v0
	v_mov_b32_e32 v52, v0
	v_mov_b32_e32 v53, v0
	v_mov_b32_e32 v54, v0
	v_mov_b32_e32 v55, v0
	v_mov_b32_e32 v8, v0
	v_mov_b32_e32 v9, v0
	v_mov_b32_e32 v10, v0
	v_mov_b32_e32 v11, v0
	v_mov_b32_e32 v12, v0
	v_mov_b32_e32 v13, v0
	v_mov_b32_e32 v14, v0
	v_mov_b32_e32 v15, v0
	v_mov_b32_e32 v24, v0
	v_mov_b32_e32 v25, v0
	v_mov_b32_e32 v26, v0
	v_mov_b32_e32 v27, v0
	v_mov_b32_e32 v28, v0
	v_mov_b32_e32 v29, v0
	v_mov_b32_e32 v30, v0
	v_mov_b32_e32 v31, v0
	v_mov_b32_e32 v40, v0
	v_mov_b32_e32 v41, v0
	v_mov_b32_e32 v42, v0
	v_mov_b32_e32 v43, v0
	v_mov_b32_e32 v44, v0
	v_mov_b32_e32 v45, v0
	v_mov_b32_e32 v46, v0
	v_mov_b32_e32 v47, v0
	v_mov_b32_e32 v56, v0
	v_mov_b32_e32 v57, v0
	v_mov_b32_e32 v58, v0
	v_mov_b32_e32 v59, v0
	v_mov_b32_e32 v60, v0
	v_mov_b32_e32 v61, v0
	v_mov_b32_e32 v62, v0
	v_mov_b32_e32 v63, v0
	v_mov_b32_e32 v64, v0
	v_mov_b32_e32 v65, v0
	v_mov_b32_e32 v66, v0
	v_mov_b32_e32 v67, v0
	v_mov_b32_e32 v68, v0
	v_mov_b32_e32 v69, v0
	v_mov_b32_e32 v70, v0
	v_mov_b32_e32 v71, v0
	v_mov_b32_e32 v80, v0
	v_mov_b32_e32 v81, v0
	v_mov_b32_e32 v82, v0
	v_mov_b32_e32 v83, v0
	v_mov_b32_e32 v84, v0
	v_mov_b32_e32 v85, v0
	v_mov_b32_e32 v86, v0
	v_mov_b32_e32 v87, v0
	v_mov_b32_e32 v96, v0
	v_mov_b32_e32 v97, v0
	v_mov_b32_e32 v98, v0
	v_mov_b32_e32 v99, v0
	v_mov_b32_e32 v100, v0
	v_mov_b32_e32 v101, v0
	v_mov_b32_e32 v102, v0
	v_mov_b32_e32 v103, v0
	v_mov_b32_e32 v112, v0
	v_mov_b32_e32 v113, v0
	v_mov_b32_e32 v114, v0
	v_mov_b32_e32 v115, v0
	v_mov_b32_e32 v116, v0
	v_mov_b32_e32 v117, v0
	v_mov_b32_e32 v118, v0
	v_mov_b32_e32 v119, v0
	v_mov_b32_e32 v72, v0
	v_mov_b32_e32 v73, v0
	v_mov_b32_e32 v74, v0
	v_mov_b32_e32 v75, v0
	v_mov_b32_e32 v76, v0
	v_mov_b32_e32 v77, v0
	v_mov_b32_e32 v78, v0
	v_mov_b32_e32 v79, v0
	v_mov_b32_e32 v88, v0
	v_mov_b32_e32 v89, v0
	v_mov_b32_e32 v90, v0
	v_mov_b32_e32 v91, v0
	v_mov_b32_e32 v92, v0
	v_mov_b32_e32 v93, v0
	v_mov_b32_e32 v94, v0
	v_mov_b32_e32 v95, v0
	v_mov_b32_e32 v104, v0
	v_mov_b32_e32 v105, v0
	v_mov_b32_e32 v106, v0
	v_mov_b32_e32 v107, v0
	v_mov_b32_e32 v108, v0
	v_mov_b32_e32 v109, v0
	v_mov_b32_e32 v110, v0
	v_mov_b32_e32 v111, v0
	v_mov_b32_e32 v120, v0
	v_mov_b32_e32 v121, v0
	v_mov_b32_e32 v122, v0
	v_mov_b32_e32 v123, v0
	v_mov_b32_e32 v124, v0
	v_mov_b32_e32 v125, v0
	v_mov_b32_e32 v126, v0
	v_mov_b32_e32 v127, v0
	s_mov_b64 s[74:75], 0x80
	s_waitcnt vmcnt(0)
	v_add_u32_e32 v234, 0x10000, v141
	v_add_u32_e32 v235, 0x14000, v141
	v_add_u32_e32 v236, 0x18000, v141
	v_add_u32_e32 v237, 0x1c000, v141
.LBB0_1383:
	s_add_u32 s16, s14, 0x100
	s_addc_u32 s17, s15, 0
	s_add_i32 s40, 0, 0x10000
	s_cmp_eq_u32 s37, 28
	s_cselect_b32 s21, s9, s17
	s_cselect_b32 s20, s33, s16
	s_cselect_b32 s19, s7, s36
	s_cselect_b32 s18, s34, s35
	s_add_i32 s41, 0, 0x14000
	ds_read_b128 v[134:137], v234
	ds_read_b128 v[144:147], v234 offset:1024
	ds_read_b128 v[148:151], v234 offset:2048
	ds_read_b128 v[162:165], v234 offset:3072
	ds_read_b128 v[166:169], v235
	ds_read_b128 v[170:173], v235 offset:1024
	ds_read_b128 v[174:177], v235 offset:2048
	ds_read_b128 v[178:181], v235 offset:3072
	s_add_i32 m0, s23, 0xc000
	ds_read_b128 v[182:185], v143
	ds_read_b128 v[186:189], v143 offset:1024
	ds_read_b128 v[190:193], v143 offset:2048
	ds_read_b128 v[194:197], v143 offset:3072
	ds_read_b128 v[198:201], v143 offset:4096
	ds_read_b128 v[202:205], v143 offset:5120
	ds_read_b128 v[214:217], v143 offset:6144
	ds_read_b128 v[218:221], v143 offset:7168
	global_load_lds_dwordx4 v132, s[14:15]
	s_add_i32 m0, s23, 0xe000
	s_nop 0
	global_load_lds_dwordx4 v130, s[14:15]
	s_waitcnt vmcnt(8)
	s_waitcnt lgkmcnt(0)
	s_barrier
	s_setprio 1
	s_waitcnt lgkmcnt(0)
	v_mfma_f32_16x16x32_bf16 v[124:127], v[134:137], v[182:185], v[124:127]
	v_mfma_f32_16x16x32_bf16 v[120:123], v[148:151], v[182:185], v[120:123]
	v_mfma_f32_16x16x32_bf16 v[108:111], v[134:137], v[190:193], v[108:111]
	v_mfma_f32_16x16x32_bf16 v[104:107], v[148:151], v[190:193], v[104:107]
	v_mfma_f32_16x16x32_bf16 v[92:95], v[134:137], v[198:201], v[92:95]
	v_mfma_f32_16x16x32_bf16 v[88:91], v[148:151], v[198:201], v[88:91]
	v_mfma_f32_16x16x32_bf16 v[76:79], v[134:137], v[214:217], v[76:79]
	v_mfma_f32_16x16x32_bf16 v[72:75], v[148:151], v[214:217], v[72:75]
	v_mfma_f32_16x16x32_bf16 v[124:127], v[144:147], v[186:189], v[124:127]
	v_mfma_f32_16x16x32_bf16 v[120:123], v[162:165], v[186:189], v[120:123]
	v_mfma_f32_16x16x32_bf16 v[108:111], v[144:147], v[194:197], v[108:111]
	v_mfma_f32_16x16x32_bf16 v[104:107], v[162:165], v[194:197], v[104:107]
	v_mfma_f32_16x16x32_bf16 v[92:95], v[144:147], v[202:205], v[92:95]
	v_mfma_f32_16x16x32_bf16 v[88:91], v[162:165], v[202:205], v[88:91]
	v_mfma_f32_16x16x32_bf16 v[76:79], v[144:147], v[218:221], v[76:79]
	v_mfma_f32_16x16x32_bf16 v[72:75], v[162:165], v[218:221], v[72:75]
	s_setprio 0
	s_setprio 1
	v_mfma_f32_16x16x32_bf16 v[116:119], v[166:169], v[182:185], v[116:119]
	v_mfma_f32_16x16x32_bf16 v[112:115], v[174:177], v[182:185], v[112:115]
	v_mfma_f32_16x16x32_bf16 v[100:103], v[166:169], v[190:193], v[100:103]
	v_mfma_f32_16x16x32_bf16 v[96:99], v[174:177], v[190:193], v[96:99]
	v_mfma_f32_16x16x32_bf16 v[84:87], v[166:169], v[198:201], v[84:87]
	v_mfma_f32_16x16x32_bf16 v[80:83], v[174:177], v[198:201], v[80:83]
	v_mfma_f32_16x16x32_bf16 v[68:71], v[166:169], v[214:217], v[68:71]
	v_mfma_f32_16x16x32_bf16 v[64:67], v[174:177], v[214:217], v[64:67]
	v_mfma_f32_16x16x32_bf16 v[116:119], v[170:173], v[186:189], v[116:119]
	v_mfma_f32_16x16x32_bf16 v[112:115], v[178:181], v[186:189], v[112:115]
	v_mfma_f32_16x16x32_bf16 v[100:103], v[170:173], v[194:197], v[100:103]
	v_mfma_f32_16x16x32_bf16 v[96:99], v[178:181], v[194:197], v[96:99]
	v_mfma_f32_16x16x32_bf16 v[84:87], v[170:173], v[202:205], v[84:87]
	v_mfma_f32_16x16x32_bf16 v[80:83], v[178:181], v[202:205], v[80:83]
	v_mfma_f32_16x16x32_bf16 v[68:71], v[170:173], v[218:221], v[68:71]
	v_mfma_f32_16x16x32_bf16 v[64:67], v[178:181], v[218:221], v[64:67]
	s_setprio 0
	s_barrier
	s_add_i32 s14, s40, s22
	s_add_u32 s100, s18, 0x80
	s_addc_u32 s101, s19, 0
	s_mov_b32 m0, s14
	ds_read_b128 v[182:185], v143 offset:16384
	ds_read_b128 v[186:189], v143 offset:17408
	ds_read_b128 v[190:193], v143 offset:18432
	ds_read_b128 v[194:197], v143 offset:19456
	ds_read_b128 v[198:201], v143 offset:20480
	ds_read_b128 v[202:205], v143 offset:21504
	ds_read_b128 v[214:217], v143 offset:22528
	ds_read_b128 v[218:221], v143 offset:23552
	global_load_lds_dwordx4 v152, s[18:19]
	s_add_i32 m0, s14, 0x2000
	s_add_u32 s14, s18, 0x80000
	s_addc_u32 s15, s19, 0
	s_add_i32 s40, s41, s22
	global_load_lds_dwordx4 v128, s[18:19]
	s_mov_b32 m0, s40
	s_nop 0
	global_load_lds_dwordx4 v152, s[14:15]
	s_add_i32 m0, s40, 0x2000
	s_nop 0
	global_load_lds_dwordx4 v128, s[14:15]
	s_add_u32 s98, s20, 0x80
	s_addc_u32 s99, s21, 0
	s_mov_b32 m0, s23
	s_nop 0
	global_load_lds_dwordx4 v152, s[20:21]
	s_mov_b32 m0, s24
	s_nop 0
	global_load_lds_dwordx4 v128, s[20:21]
	s_waitcnt vmcnt(8)
	s_waitcnt lgkmcnt(0)
	s_barrier
	s_setprio 1
	s_waitcnt lgkmcnt(0)
	v_mfma_f32_16x16x32_bf16 v[60:63], v[134:137], v[182:185], v[60:63]
	v_mfma_f32_16x16x32_bf16 v[56:59], v[148:151], v[182:185], v[56:59]
	v_mfma_f32_16x16x32_bf16 v[44:47], v[134:137], v[190:193], v[44:47]
	v_mfma_f32_16x16x32_bf16 v[40:43], v[148:151], v[190:193], v[40:43]
	v_mfma_f32_16x16x32_bf16 v[28:31], v[134:137], v[198:201], v[28:31]
	v_mfma_f32_16x16x32_bf16 v[24:27], v[148:151], v[198:201], v[24:27]
	v_mfma_f32_16x16x32_bf16 v[12:15], v[134:137], v[214:217], v[12:15]
	v_mfma_f32_16x16x32_bf16 v[8:11], v[148:151], v[214:217], v[8:11]
	v_mfma_f32_16x16x32_bf16 v[60:63], v[144:147], v[186:189], v[60:63]
	v_mfma_f32_16x16x32_bf16 v[56:59], v[162:165], v[186:189], v[56:59]
	v_mfma_f32_16x16x32_bf16 v[44:47], v[144:147], v[194:197], v[44:47]
	v_mfma_f32_16x16x32_bf16 v[40:43], v[162:165], v[194:197], v[40:43]
	v_mfma_f32_16x16x32_bf16 v[28:31], v[144:147], v[202:205], v[28:31]
	v_mfma_f32_16x16x32_bf16 v[24:27], v[162:165], v[202:205], v[24:27]
	v_mfma_f32_16x16x32_bf16 v[12:15], v[144:147], v[218:221], v[12:15]
	v_mfma_f32_16x16x32_bf16 v[8:11], v[162:165], v[218:221], v[8:11]
	s_setprio 0
	s_setprio 1
	v_mfma_f32_16x16x32_bf16 v[52:55], v[166:169], v[182:185], v[52:55]
	v_mfma_f32_16x16x32_bf16 v[48:51], v[174:177], v[182:185], v[48:51]
	v_mfma_f32_16x16x32_bf16 v[36:39], v[166:169], v[190:193], v[36:39]
	v_mfma_f32_16x16x32_bf16 v[32:35], v[174:177], v[190:193], v[32:35]
	v_mfma_f32_16x16x32_bf16 v[20:23], v[166:169], v[198:201], v[20:23]
	v_mfma_f32_16x16x32_bf16 v[16:19], v[174:177], v[198:201], v[16:19]
	v_mfma_f32_16x16x32_bf16 v[4:7], v[166:169], v[214:217], v[4:7]
	v_mfma_f32_16x16x32_bf16 v[0:3], v[174:177], v[214:217], v[0:3]
	v_mfma_f32_16x16x32_bf16 v[52:55], v[170:173], v[186:189], v[52:55]
	v_mfma_f32_16x16x32_bf16 v[48:51], v[178:181], v[186:189], v[48:51]
	v_mfma_f32_16x16x32_bf16 v[36:39], v[170:173], v[194:197], v[36:39]
	v_mfma_f32_16x16x32_bf16 v[32:35], v[178:181], v[194:197], v[32:35]
	v_mfma_f32_16x16x32_bf16 v[20:23], v[170:173], v[202:205], v[20:23]
	v_mfma_f32_16x16x32_bf16 v[16:19], v[178:181], v[202:205], v[16:19]
	v_mfma_f32_16x16x32_bf16 v[4:7], v[170:173], v[218:221], v[4:7]
	v_mfma_f32_16x16x32_bf16 v[0:3], v[178:181], v[218:221], v[0:3]
	s_setprio 0
	s_barrier
	s_add_i32 s40, 0, 0x18000
	s_add_i32 s41, 0, 0x1c000
	ds_read_b128 v[134:137], v236
	ds_read_b128 v[144:147], v236 offset:1024
	ds_read_b128 v[148:151], v236 offset:2048
	ds_read_b128 v[162:165], v236 offset:3072
	ds_read_b128 v[166:169], v237
	ds_read_b128 v[170:173], v237 offset:1024
	ds_read_b128 v[174:177], v237 offset:2048
	ds_read_b128 v[178:181], v237 offset:3072
	s_add_u32 s14, s20, 0x80000
	s_addc_u32 s15, s21, 0
	s_mov_b32 m0, s25
	ds_read_b128 v[182:185], v143 offset:32768
	ds_read_b128 v[186:189], v143 offset:33792
	ds_read_b128 v[190:193], v143 offset:34816
	ds_read_b128 v[194:197], v143 offset:35840
	ds_read_b128 v[198:201], v143 offset:36864
	ds_read_b128 v[202:205], v143 offset:37888
	ds_read_b128 v[214:217], v143 offset:38912
	ds_read_b128 v[218:221], v143 offset:39936
	global_load_lds_dwordx4 v152, s[14:15]
	s_mov_b32 m0, s26
	s_nop 0
	global_load_lds_dwordx4 v128, s[14:15]
	s_waitcnt vmcnt(8)
	s_waitcnt lgkmcnt(0)
	s_barrier
	s_setprio 1
	s_waitcnt lgkmcnt(0)
	v_mfma_f32_16x16x32_bf16 v[124:127], v[134:137], v[182:185], v[124:127]
	v_mfma_f32_16x16x32_bf16 v[120:123], v[148:151], v[182:185], v[120:123]
	v_mfma_f32_16x16x32_bf16 v[108:111], v[134:137], v[190:193], v[108:111]
	v_mfma_f32_16x16x32_bf16 v[104:107], v[148:151], v[190:193], v[104:107]
	v_mfma_f32_16x16x32_bf16 v[92:95], v[134:137], v[198:201], v[92:95]
	v_mfma_f32_16x16x32_bf16 v[88:91], v[148:151], v[198:201], v[88:91]
	v_mfma_f32_16x16x32_bf16 v[76:79], v[134:137], v[214:217], v[76:79]
	v_mfma_f32_16x16x32_bf16 v[72:75], v[148:151], v[214:217], v[72:75]
	v_mfma_f32_16x16x32_bf16 v[124:127], v[144:147], v[186:189], v[124:127]
	v_mfma_f32_16x16x32_bf16 v[120:123], v[162:165], v[186:189], v[120:123]
	v_mfma_f32_16x16x32_bf16 v[108:111], v[144:147], v[194:197], v[108:111]
	v_mfma_f32_16x16x32_bf16 v[104:107], v[162:165], v[194:197], v[104:107]
	v_mfma_f32_16x16x32_bf16 v[92:95], v[144:147], v[202:205], v[92:95]
	v_mfma_f32_16x16x32_bf16 v[88:91], v[162:165], v[202:205], v[88:91]
	v_mfma_f32_16x16x32_bf16 v[76:79], v[144:147], v[218:221], v[76:79]
	v_mfma_f32_16x16x32_bf16 v[72:75], v[162:165], v[218:221], v[72:75]
	s_setprio 0
	s_setprio 1
	v_mfma_f32_16x16x32_bf16 v[116:119], v[166:169], v[182:185], v[116:119]
	v_mfma_f32_16x16x32_bf16 v[112:115], v[174:177], v[182:185], v[112:115]
	v_mfma_f32_16x16x32_bf16 v[100:103], v[166:169], v[190:193], v[100:103]
	v_mfma_f32_16x16x32_bf16 v[96:99], v[174:177], v[190:193], v[96:99]
	v_mfma_f32_16x16x32_bf16 v[84:87], v[166:169], v[198:201], v[84:87]
	v_mfma_f32_16x16x32_bf16 v[80:83], v[174:177], v[198:201], v[80:83]
	v_mfma_f32_16x16x32_bf16 v[68:71], v[166:169], v[214:217], v[68:71]
	v_mfma_f32_16x16x32_bf16 v[64:67], v[174:177], v[214:217], v[64:67]
	v_mfma_f32_16x16x32_bf16 v[116:119], v[170:173], v[186:189], v[116:119]
	v_mfma_f32_16x16x32_bf16 v[112:115], v[178:181], v[186:189], v[112:115]
	v_mfma_f32_16x16x32_bf16 v[100:103], v[170:173], v[194:197], v[100:103]
	v_mfma_f32_16x16x32_bf16 v[96:99], v[178:181], v[194:197], v[96:99]
	v_mfma_f32_16x16x32_bf16 v[84:87], v[170:173], v[202:205], v[84:87]
	v_mfma_f32_16x16x32_bf16 v[80:83], v[178:181], v[202:205], v[80:83]
	v_mfma_f32_16x16x32_bf16 v[68:71], v[170:173], v[218:221], v[68:71]
	v_mfma_f32_16x16x32_bf16 v[64:67], v[178:181], v[218:221], v[64:67]
	s_setprio 0
	s_barrier
	s_add_i32 s14, s40, s22
	s_mov_b32 m0, s14
	ds_read_b128 v[182:185], v143 offset:49152
	ds_read_b128 v[186:189], v143 offset:50176
	ds_read_b128 v[190:193], v143 offset:51200
	ds_read_b128 v[194:197], v143 offset:52224
	ds_read_b128 v[198:201], v143 offset:53248
	ds_read_b128 v[202:205], v143 offset:54272
	ds_read_b128 v[214:217], v143 offset:55296
	ds_read_b128 v[218:221], v143 offset:56320
	global_load_lds_dwordx4 v152, s[100:101]
	s_add_i32 m0, s14, 0x2000
	s_add_u32 s14, s18, 0x80080
	s_addc_u32 s15, s19, 0
	s_add_i32 s18, s41, s22
	global_load_lds_dwordx4 v128, s[100:101]
	s_mov_b32 m0, s18
	s_nop 0
	global_load_lds_dwordx4 v152, s[14:15]
	s_add_i32 m0, s18, 0x2000
	s_nop 0
	global_load_lds_dwordx4 v128, s[14:15]
	s_mov_b32 m0, s27
	s_nop 0
	global_load_lds_dwordx4 v152, s[98:99]
	s_mov_b32 m0, s28
	s_nop 0
	global_load_lds_dwordx4 v128, s[98:99]
	s_waitcnt vmcnt(8)
	s_waitcnt lgkmcnt(0)
	s_barrier
	s_setprio 1
	s_waitcnt lgkmcnt(0)
	v_mfma_f32_16x16x32_bf16 v[60:63], v[134:137], v[182:185], v[60:63]
	v_mfma_f32_16x16x32_bf16 v[56:59], v[148:151], v[182:185], v[56:59]
	v_mfma_f32_16x16x32_bf16 v[44:47], v[134:137], v[190:193], v[44:47]
	v_mfma_f32_16x16x32_bf16 v[40:43], v[148:151], v[190:193], v[40:43]
	v_mfma_f32_16x16x32_bf16 v[28:31], v[134:137], v[198:201], v[28:31]
	v_mfma_f32_16x16x32_bf16 v[24:27], v[148:151], v[198:201], v[24:27]
	v_mfma_f32_16x16x32_bf16 v[12:15], v[134:137], v[214:217], v[12:15]
	v_mfma_f32_16x16x32_bf16 v[8:11], v[148:151], v[214:217], v[8:11]
	v_mfma_f32_16x16x32_bf16 v[60:63], v[144:147], v[186:189], v[60:63]
	v_mfma_f32_16x16x32_bf16 v[56:59], v[162:165], v[186:189], v[56:59]
	v_mfma_f32_16x16x32_bf16 v[44:47], v[144:147], v[194:197], v[44:47]
	v_mfma_f32_16x16x32_bf16 v[40:43], v[162:165], v[194:197], v[40:43]
	v_mfma_f32_16x16x32_bf16 v[28:31], v[144:147], v[202:205], v[28:31]
	v_mfma_f32_16x16x32_bf16 v[24:27], v[162:165], v[202:205], v[24:27]
	v_mfma_f32_16x16x32_bf16 v[12:15], v[144:147], v[218:221], v[12:15]
	v_mfma_f32_16x16x32_bf16 v[8:11], v[162:165], v[218:221], v[8:11]
	s_setprio 0
	s_setprio 1
	v_mfma_f32_16x16x32_bf16 v[52:55], v[166:169], v[182:185], v[52:55]
	v_mfma_f32_16x16x32_bf16 v[48:51], v[174:177], v[182:185], v[48:51]
	v_mfma_f32_16x16x32_bf16 v[36:39], v[166:169], v[190:193], v[36:39]
	v_mfma_f32_16x16x32_bf16 v[32:35], v[174:177], v[190:193], v[32:35]
	v_mfma_f32_16x16x32_bf16 v[20:23], v[166:169], v[198:201], v[20:23]
	v_mfma_f32_16x16x32_bf16 v[16:19], v[174:177], v[198:201], v[16:19]
	v_mfma_f32_16x16x32_bf16 v[4:7], v[166:169], v[214:217], v[4:7]
	v_mfma_f32_16x16x32_bf16 v[0:3], v[174:177], v[214:217], v[0:3]
	v_mfma_f32_16x16x32_bf16 v[52:55], v[170:173], v[186:189], v[52:55]
	v_mfma_f32_16x16x32_bf16 v[48:51], v[178:181], v[186:189], v[48:51]
	v_mfma_f32_16x16x32_bf16 v[36:39], v[170:173], v[194:197], v[36:39]
	v_mfma_f32_16x16x32_bf16 v[32:35], v[178:181], v[194:197], v[32:35]
	v_mfma_f32_16x16x32_bf16 v[20:23], v[170:173], v[202:205], v[20:23]
	v_mfma_f32_16x16x32_bf16 v[16:19], v[178:181], v[202:205], v[16:19]
	v_mfma_f32_16x16x32_bf16 v[4:7], v[170:173], v[218:221], v[4:7]
	v_mfma_f32_16x16x32_bf16 v[0:3], v[178:181], v[218:221], v[0:3]
	s_setprio 0
	s_barrier
	s_add_i32 s37, s37, 2
	s_add_u32 s35, s35, 0x100
	s_addc_u32 s36, s36, 0
	s_cmp_gt_u32 s37, 29
	s_mov_b64 s[14:15], s[16:17]
	s_cbranch_scc0 .LBB0_1383
	s_and_b64 vcc, exec, s[4:5]
	s_cbranch_vccz .LBB0_1386
	s_barrier

.LBB0_1509:
	s_ashr_i32 s9, s8, 31
	s_lshl_b64 s[10:11], s[8:9], 20
	s_add_u32 s10, s66, s10
	s_addc_u32 s11, s67, s11
	s_and_b64 s[12:13], s[0:1], exec
	s_cselect_b32 s9, s11, s15
	s_cselect_b32 s30, s10, s14
	s_ashr_i32 s7, s6, 31
	s_lshl_b64 s[12:13], s[6:7], 20
	s_add_u32 s12, s62, s12
	s_addc_u32 s13, s63, s13
	s_and_b64 s[18:19], s[0:1], exec
	s_cselect_b32 s7, s13, s17
	s_cselect_b32 s31, s12, s16
	s_add_u32 s33, s16, 0x100
	s_addc_u32 s34, s17, 0
	s_add_u32 s14, s14, 0x80080
	v_mov_b32_e32 v0, 0
	s_addc_u32 s15, s15, 0
	s_mov_b32 s35, -2
	v_mov_b32_e32 v1, v0
	v_mov_b32_e32 v2, v0
	v_mov_b32_e32 v3, v0
	v_mov_b32_e32 v8, v0
	v_mov_b32_e32 v9, v0
	v_mov_b32_e32 v10, v0
	v_mov_b32_e32 v11, v0
	v_mov_b32_e32 v16, v0
	v_mov_b32_e32 v17, v0
	v_mov_b32_e32 v18, v0
	v_mov_b32_e32 v19, v0
	v_mov_b32_e32 v24, v0
	v_mov_b32_e32 v25, v0
	v_mov_b32_e32 v26, v0
	v_mov_b32_e32 v27, v0
	v_mov_b32_e32 v32, v0
	v_mov_b32_e32 v33, v0
	v_mov_b32_e32 v34, v0
	v_mov_b32_e32 v35, v0
	v_mov_b32_e32 v40, v0
	v_mov_b32_e32 v41, v0
	v_mov_b32_e32 v42, v0
	v_mov_b32_e32 v43, v0
	v_mov_b32_e32 v48, v0
	v_mov_b32_e32 v49, v0
	v_mov_b32_e32 v50, v0
	v_mov_b32_e32 v51, v0
	v_mov_b32_e32 v56, v0
	v_mov_b32_e32 v57, v0
	v_mov_b32_e32 v58, v0
	v_mov_b32_e32 v59, v0
	v_mov_b32_e32 v4, v0
	v_mov_b32_e32 v5, v0
	v_mov_b32_e32 v6, v0
	v_mov_b32_e32 v7, v0
	v_mov_b32_e32 v12, v0
	v_mov_b32_e32 v13, v0
	v_mov_b32_e32 v14, v0
	v_mov_b32_e32 v15, v0
	v_mov_b32_e32 v20, v0
	v_mov_b32_e32 v21, v0
	v_mov_b32_e32 v22, v0
	v_mov_b32_e32 v23, v0
	v_mov_b32_e32 v28, v0
	v_mov_b32_e32 v29, v0
	v_mov_b32_e32 v30, v0
	v_mov_b32_e32 v31, v0
	v_mov_b32_e32 v36, v0
	v_mov_b32_e32 v37, v0
	v_mov_b32_e32 v38, v0
	v_mov_b32_e32 v39, v0
	v_mov_b32_e32 v44, v0
	v_mov_b32_e32 v45, v0
	v_mov_b32_e32 v46, v0
	v_mov_b32_e32 v47, v0
	v_mov_b32_e32 v52, v0
	v_mov_b32_e32 v53, v0
	v_mov_b32_e32 v54, v0
	v_mov_b32_e32 v55, v0
	v_mov_b32_e32 v60, v0
	v_mov_b32_e32 v61, v0
	v_mov_b32_e32 v62, v0
	v_mov_b32_e32 v63, v0
	v_mov_b32_e32 v64, v0
	v_mov_b32_e32 v65, v0
	v_mov_b32_e32 v66, v0
	v_mov_b32_e32 v67, v0
	v_mov_b32_e32 v72, v0
	v_mov_b32_e32 v73, v0
	v_mov_b32_e32 v74, v0
	v_mov_b32_e32 v75, v0
	v_mov_b32_e32 v80, v0
	v_mov_b32_e32 v81, v0
	v_mov_b32_e32 v82, v0
	v_mov_b32_e32 v83, v0
	v_mov_b32_e32 v88, v0
	v_mov_b32_e32 v89, v0
	v_mov_b32_e32 v90, v0
	v_mov_b32_e32 v91, v0
	v_mov_b32_e32 v96, v0
	v_mov_b32_e32 v97, v0
	v_mov_b32_e32 v98, v0
	v_mov_b32_e32 v99, v0
	v_mov_b32_e32 v104, v0
	v_mov_b32_e32 v105, v0
	v_mov_b32_e32 v106, v0
	v_mov_b32_e32 v107, v0
	v_mov_b32_e32 v112, v0
	v_mov_b32_e32 v113, v0
	v_mov_b32_e32 v114, v0
	v_mov_b32_e32 v115, v0
	v_mov_b32_e32 v120, v0
	v_mov_b32_e32 v121, v0
	v_mov_b32_e32 v122, v0
	v_mov_b32_e32 v123, v0
	v_mov_b32_e32 v68, v0
	v_mov_b32_e32 v69, v0
	v_mov_b32_e32 v70, v0
	v_mov_b32_e32 v71, v0
	v_mov_b32_e32 v76, v0
	v_mov_b32_e32 v77, v0
	v_mov_b32_e32 v78, v0
	v_mov_b32_e32 v79, v0
	v_mov_b32_e32 v84, v0
	v_mov_b32_e32 v85, v0
	v_mov_b32_e32 v86, v0
	v_mov_b32_e32 v87, v0
	v_mov_b32_e32 v92, v0
	v_mov_b32_e32 v93, v0
	v_mov_b32_e32 v94, v0
	v_mov_b32_e32 v95, v0
	v_mov_b32_e32 v100, v0
	v_mov_b32_e32 v101, v0
	v_mov_b32_e32 v102, v0
	v_mov_b32_e32 v103, v0
	v_mov_b32_e32 v108, v0
	v_mov_b32_e32 v109, v0
	v_mov_b32_e32 v110, v0
	v_mov_b32_e32 v111, v0
	v_mov_b32_e32 v116, v0
	v_mov_b32_e32 v117, v0
	v_mov_b32_e32 v118, v0
	v_mov_b32_e32 v119, v0
	v_mov_b32_e32 v124, v0
	v_mov_b32_e32 v125, v0
	v_mov_b32_e32 v126, v0
	v_mov_b32_e32 v127, v0
	s_mov_b64 s[74:75], 0x80
	v_add_u32_e32 v234, 0x10000, v141
	v_add_u32_e32 v235, 0x14000, v141
	v_add_u32_e32 v236, 0x18000, v141
	v_add_u32_e32 v237, 0x1c000, v141
.LBB0_1510:
	s_add_u32 s16, s14, 0xfff80080
	s_addc_u32 s17, s15, -1
	s_add_i32 s36, 0, 0x10000
	s_cmp_eq_u32 s35, 28
	s_cselect_b32 s19, s9, s17
	s_cselect_b32 s18, s30, s16
	s_cselect_b32 s17, s7, s34
	s_cselect_b32 s16, s31, s33
	s_add_i32 s40, 0, 0x14000
	ds_read_b128 v[144:147], v234
	ds_read_b128 v[148:151], v234 offset:1024
	ds_read_b128 v[162:165], v234 offset:2048
	ds_read_b128 v[166:169], v234 offset:3072
	ds_read_b128 v[170:173], v235
	ds_read_b128 v[174:177], v235 offset:1024
	ds_read_b128 v[178:181], v235 offset:2048
	ds_read_b128 v[182:185], v235 offset:3072
	s_add_i32 m0, s21, 0xc000
	ds_read_b128 v[186:189], v143
	ds_read_b128 v[190:193], v143 offset:1024
	ds_read_b128 v[194:197], v143 offset:2048
	ds_read_b128 v[198:201], v143 offset:3072
	ds_read_b128 v[202:205], v143 offset:4096
	ds_read_b128 v[214:217], v143 offset:5120
	ds_read_b128 v[218:221], v143 offset:6144
	ds_read_b128 v[222:225], v143 offset:7168
	global_load_lds_dwordx4 v136, s[14:15]
	s_add_i32 m0, s21, 0xe000
	s_nop 0
	global_load_lds_dwordx4 v134, s[14:15]
	s_waitcnt vmcnt(8)
	s_waitcnt lgkmcnt(0)
	s_barrier
	s_setprio 1
	s_waitcnt lgkmcnt(0)
	v_mfma_f32_16x16x32_bf16 v[124:127], v[144:147], v[186:189], v[124:127]
	v_mfma_f32_16x16x32_bf16 v[116:119], v[162:165], v[186:189], v[116:119]
	v_mfma_f32_16x16x32_bf16 v[108:111], v[144:147], v[194:197], v[108:111]
	v_mfma_f32_16x16x32_bf16 v[100:103], v[162:165], v[194:197], v[100:103]
	v_mfma_f32_16x16x32_bf16 v[92:95], v[144:147], v[202:205], v[92:95]
	v_mfma_f32_16x16x32_bf16 v[84:87], v[162:165], v[202:205], v[84:87]
	v_mfma_f32_16x16x32_bf16 v[76:79], v[144:147], v[218:221], v[76:79]
	v_mfma_f32_16x16x32_bf16 v[68:71], v[162:165], v[218:221], v[68:71]
	v_mfma_f32_16x16x32_bf16 v[124:127], v[148:151], v[190:193], v[124:127]
	v_mfma_f32_16x16x32_bf16 v[116:119], v[166:169], v[190:193], v[116:119]
	v_mfma_f32_16x16x32_bf16 v[108:111], v[148:151], v[198:201], v[108:111]
	v_mfma_f32_16x16x32_bf16 v[100:103], v[166:169], v[198:201], v[100:103]
	v_mfma_f32_16x16x32_bf16 v[92:95], v[148:151], v[214:217], v[92:95]
	v_mfma_f32_16x16x32_bf16 v[84:87], v[166:169], v[214:217], v[84:87]
	v_mfma_f32_16x16x32_bf16 v[76:79], v[148:151], v[222:225], v[76:79]
	v_mfma_f32_16x16x32_bf16 v[68:71], v[166:169], v[222:225], v[68:71]
	s_setprio 0
	s_setprio 1
	v_mfma_f32_16x16x32_bf16 v[120:123], v[170:173], v[186:189], v[120:123]
	v_mfma_f32_16x16x32_bf16 v[112:115], v[178:181], v[186:189], v[112:115]
	v_mfma_f32_16x16x32_bf16 v[104:107], v[170:173], v[194:197], v[104:107]
	v_mfma_f32_16x16x32_bf16 v[96:99], v[178:181], v[194:197], v[96:99]
	v_mfma_f32_16x16x32_bf16 v[88:91], v[170:173], v[202:205], v[88:91]
	v_mfma_f32_16x16x32_bf16 v[80:83], v[178:181], v[202:205], v[80:83]
	v_mfma_f32_16x16x32_bf16 v[72:75], v[170:173], v[218:221], v[72:75]
	v_mfma_f32_16x16x32_bf16 v[64:67], v[178:181], v[218:221], v[64:67]
	v_mfma_f32_16x16x32_bf16 v[120:123], v[174:177], v[190:193], v[120:123]
	v_mfma_f32_16x16x32_bf16 v[112:115], v[182:185], v[190:193], v[112:115]
	v_mfma_f32_16x16x32_bf16 v[104:107], v[174:177], v[198:201], v[104:107]
	v_mfma_f32_16x16x32_bf16 v[96:99], v[182:185], v[198:201], v[96:99]
	v_mfma_f32_16x16x32_bf16 v[88:91], v[174:177], v[214:217], v[88:91]
	v_mfma_f32_16x16x32_bf16 v[80:83], v[182:185], v[214:217], v[80:83]
	v_mfma_f32_16x16x32_bf16 v[72:75], v[174:177], v[222:225], v[72:75]
	v_mfma_f32_16x16x32_bf16 v[64:67], v[182:185], v[222:225], v[64:67]
	s_setprio 0
	s_barrier
	s_add_i32 s36, s36, s20
	s_add_u32 s100, s16, 0x80
	s_addc_u32 s101, s17, 0
	s_mov_b32 m0, s36
	ds_read_b128 v[186:189], v143 offset:16384
	ds_read_b128 v[190:193], v143 offset:17408
	ds_read_b128 v[194:197], v143 offset:18432
	ds_read_b128 v[198:201], v143 offset:19456
	ds_read_b128 v[202:205], v143 offset:20480
	ds_read_b128 v[214:217], v143 offset:21504
	ds_read_b128 v[218:221], v143 offset:22528
	ds_read_b128 v[222:225], v143 offset:23552
	global_load_lds_dwordx4 v152, s[16:17]
	s_add_i32 m0, s36, 0x2000
	s_add_u32 s36, s16, 0x80000
	s_addc_u32 s37, s17, 0
	s_add_i32 s40, s40, s20
	global_load_lds_dwordx4 v128, s[16:17]
	s_mov_b32 m0, s40
	s_nop 0
	global_load_lds_dwordx4 v152, s[36:37]
	s_add_i32 m0, s40, 0x2000
	s_nop 0
	global_load_lds_dwordx4 v128, s[36:37]
	s_add_u32 s98, s18, 0x80
	s_addc_u32 s99, s19, 0
	s_mov_b32 m0, s21
	s_nop 0
	global_load_lds_dwordx4 v132, s[18:19]
	s_mov_b32 m0, s22
	s_nop 0
	global_load_lds_dwordx4 v130, s[18:19]
	s_waitcnt vmcnt(8)
	s_waitcnt lgkmcnt(0)
	s_barrier
	s_setprio 1
	s_waitcnt lgkmcnt(0)
	v_mfma_f32_16x16x32_bf16 v[60:63], v[144:147], v[186:189], v[60:63]
	v_mfma_f32_16x16x32_bf16 v[52:55], v[162:165], v[186:189], v[52:55]
	v_mfma_f32_16x16x32_bf16 v[44:47], v[144:147], v[194:197], v[44:47]
	v_mfma_f32_16x16x32_bf16 v[36:39], v[162:165], v[194:197], v[36:39]
	v_mfma_f32_16x16x32_bf16 v[28:31], v[144:147], v[202:205], v[28:31]
	v_mfma_f32_16x16x32_bf16 v[20:23], v[162:165], v[202:205], v[20:23]
	v_mfma_f32_16x16x32_bf16 v[12:15], v[144:147], v[218:221], v[12:15]
	v_mfma_f32_16x16x32_bf16 v[4:7], v[162:165], v[218:221], v[4:7]
	v_mfma_f32_16x16x32_bf16 v[60:63], v[148:151], v[190:193], v[60:63]
	v_mfma_f32_16x16x32_bf16 v[52:55], v[166:169], v[190:193], v[52:55]
	v_mfma_f32_16x16x32_bf16 v[44:47], v[148:151], v[198:201], v[44:47]
	v_mfma_f32_16x16x32_bf16 v[36:39], v[166:169], v[198:201], v[36:39]
	v_mfma_f32_16x16x32_bf16 v[28:31], v[148:151], v[214:217], v[28:31]
	v_mfma_f32_16x16x32_bf16 v[20:23], v[166:169], v[214:217], v[20:23]
	v_mfma_f32_16x16x32_bf16 v[12:15], v[148:151], v[222:225], v[12:15]
	v_mfma_f32_16x16x32_bf16 v[4:7], v[166:169], v[222:225], v[4:7]
	s_setprio 0
	s_setprio 1
	v_mfma_f32_16x16x32_bf16 v[56:59], v[170:173], v[186:189], v[56:59]
	v_mfma_f32_16x16x32_bf16 v[48:51], v[178:181], v[186:189], v[48:51]
	v_mfma_f32_16x16x32_bf16 v[40:43], v[170:173], v[194:197], v[40:43]
	v_mfma_f32_16x16x32_bf16 v[32:35], v[178:181], v[194:197], v[32:35]
	v_mfma_f32_16x16x32_bf16 v[24:27], v[170:173], v[202:205], v[24:27]
	v_mfma_f32_16x16x32_bf16 v[16:19], v[178:181], v[202:205], v[16:19]
	v_mfma_f32_16x16x32_bf16 v[8:11], v[170:173], v[218:221], v[8:11]
	v_mfma_f32_16x16x32_bf16 v[0:3], v[178:181], v[218:221], v[0:3]
	v_mfma_f32_16x16x32_bf16 v[56:59], v[174:177], v[190:193], v[56:59]
	v_mfma_f32_16x16x32_bf16 v[48:51], v[182:185], v[190:193], v[48:51]
	v_mfma_f32_16x16x32_bf16 v[40:43], v[174:177], v[198:201], v[40:43]
	v_mfma_f32_16x16x32_bf16 v[32:35], v[182:185], v[198:201], v[32:35]
	v_mfma_f32_16x16x32_bf16 v[24:27], v[174:177], v[214:217], v[24:27]
	v_mfma_f32_16x16x32_bf16 v[16:19], v[182:185], v[214:217], v[16:19]
	v_mfma_f32_16x16x32_bf16 v[8:11], v[174:177], v[222:225], v[8:11]
	v_mfma_f32_16x16x32_bf16 v[0:3], v[182:185], v[222:225], v[0:3]
	s_setprio 0
	s_barrier
	s_add_i32 s36, 0, 0x18000
	s_add_i32 s37, 0, 0x1c000
	ds_read_b128 v[144:147], v236
	ds_read_b128 v[148:151], v236 offset:1024
	ds_read_b128 v[162:165], v236 offset:2048
	ds_read_b128 v[166:169], v236 offset:3072
	ds_read_b128 v[170:173], v237
	ds_read_b128 v[174:177], v237 offset:1024
	ds_read_b128 v[178:181], v237 offset:2048
	ds_read_b128 v[182:185], v237 offset:3072
	s_add_u32 s18, s18, 0x80000
	s_addc_u32 s19, s19, 0
	s_mov_b32 m0, s23
	ds_read_b128 v[186:189], v143 offset:32768
	ds_read_b128 v[190:193], v143 offset:33792
	ds_read_b128 v[194:197], v143 offset:34816
	ds_read_b128 v[198:201], v143 offset:35840
	ds_read_b128 v[202:205], v143 offset:36864
	ds_read_b128 v[214:217], v143 offset:37888
	ds_read_b128 v[218:221], v143 offset:38912
	ds_read_b128 v[222:225], v143 offset:39936
	global_load_lds_dwordx4 v132, s[18:19]
	s_mov_b32 m0, s24
	s_nop 0
	global_load_lds_dwordx4 v130, s[18:19]
	s_waitcnt vmcnt(8)
	s_waitcnt lgkmcnt(0)
	s_barrier
	s_setprio 1
	s_waitcnt lgkmcnt(0)
	v_mfma_f32_16x16x32_bf16 v[124:127], v[144:147], v[186:189], v[124:127]
	v_mfma_f32_16x16x32_bf16 v[116:119], v[162:165], v[186:189], v[116:119]
	v_mfma_f32_16x16x32_bf16 v[108:111], v[144:147], v[194:197], v[108:111]
	v_mfma_f32_16x16x32_bf16 v[100:103], v[162:165], v[194:197], v[100:103]
	v_mfma_f32_16x16x32_bf16 v[92:95], v[144:147], v[202:205], v[92:95]
	v_mfma_f32_16x16x32_bf16 v[84:87], v[162:165], v[202:205], v[84:87]
	v_mfma_f32_16x16x32_bf16 v[76:79], v[144:147], v[218:221], v[76:79]
	v_mfma_f32_16x16x32_bf16 v[68:71], v[162:165], v[218:221], v[68:71]
	v_mfma_f32_16x16x32_bf16 v[124:127], v[148:151], v[190:193], v[124:127]
	v_mfma_f32_16x16x32_bf16 v[116:119], v[166:169], v[190:193], v[116:119]
	v_mfma_f32_16x16x32_bf16 v[108:111], v[148:151], v[198:201], v[108:111]
	v_mfma_f32_16x16x32_bf16 v[100:103], v[166:169], v[198:201], v[100:103]
	v_mfma_f32_16x16x32_bf16 v[92:95], v[148:151], v[214:217], v[92:95]
	v_mfma_f32_16x16x32_bf16 v[84:87], v[166:169], v[214:217], v[84:87]
	v_mfma_f32_16x16x32_bf16 v[76:79], v[148:151], v[222:225], v[76:79]
	v_mfma_f32_16x16x32_bf16 v[68:71], v[166:169], v[222:225], v[68:71]
	s_setprio 0
	s_setprio 1
	v_mfma_f32_16x16x32_bf16 v[120:123], v[170:173], v[186:189], v[120:123]
	v_mfma_f32_16x16x32_bf16 v[112:115], v[178:181], v[186:189], v[112:115]
	v_mfma_f32_16x16x32_bf16 v[104:107], v[170:173], v[194:197], v[104:107]
	v_mfma_f32_16x16x32_bf16 v[96:99], v[178:181], v[194:197], v[96:99]
	v_mfma_f32_16x16x32_bf16 v[88:91], v[170:173], v[202:205], v[88:91]
	v_mfma_f32_16x16x32_bf16 v[80:83], v[178:181], v[202:205], v[80:83]
	v_mfma_f32_16x16x32_bf16 v[72:75], v[170:173], v[218:221], v[72:75]
	v_mfma_f32_16x16x32_bf16 v[64:67], v[178:181], v[218:221], v[64:67]
	v_mfma_f32_16x16x32_bf16 v[120:123], v[174:177], v[190:193], v[120:123]
	v_mfma_f32_16x16x32_bf16 v[112:115], v[182:185], v[190:193], v[112:115]
	v_mfma_f32_16x16x32_bf16 v[104:107], v[174:177], v[198:201], v[104:107]
	v_mfma_f32_16x16x32_bf16 v[96:99], v[182:185], v[198:201], v[96:99]
	v_mfma_f32_16x16x32_bf16 v[88:91], v[174:177], v[214:217], v[88:91]
	v_mfma_f32_16x16x32_bf16 v[80:83], v[182:185], v[214:217], v[80:83]
	v_mfma_f32_16x16x32_bf16 v[72:75], v[174:177], v[222:225], v[72:75]
	v_mfma_f32_16x16x32_bf16 v[64:67], v[182:185], v[222:225], v[64:67]
	s_setprio 0
	s_barrier
	s_add_i32 s18, s36, s20
	s_mov_b32 m0, s18
	ds_read_b128 v[186:189], v143 offset:49152
	ds_read_b128 v[190:193], v143 offset:50176
	ds_read_b128 v[194:197], v143 offset:51200
	ds_read_b128 v[198:201], v143 offset:52224
	ds_read_b128 v[202:205], v143 offset:53248
	ds_read_b128 v[214:217], v143 offset:54272
	ds_read_b128 v[218:221], v143 offset:55296
	ds_read_b128 v[222:225], v143 offset:56320
	global_load_lds_dwordx4 v152, s[100:101]
	s_add_i32 m0, s18, 0x2000
	s_add_u32 s16, s16, 0x80080
	s_addc_u32 s17, s17, 0
	s_add_i32 s18, s37, s20
	global_load_lds_dwordx4 v128, s[100:101]
	s_mov_b32 m0, s18
	s_nop 0
	global_load_lds_dwordx4 v152, s[16:17]
	s_add_i32 m0, s18, 0x2000
	s_nop 0
	global_load_lds_dwordx4 v128, s[16:17]
	s_mov_b32 m0, s25
	s_nop 0
	global_load_lds_dwordx4 v132, s[98:99]
	s_mov_b32 m0, s26
	s_nop 0
	global_load_lds_dwordx4 v130, s[98:99]
	s_waitcnt vmcnt(8)
	s_waitcnt lgkmcnt(0)
	s_barrier
	s_setprio 1
	s_waitcnt lgkmcnt(0)
	v_mfma_f32_16x16x32_bf16 v[60:63], v[144:147], v[186:189], v[60:63]
	v_mfma_f32_16x16x32_bf16 v[52:55], v[162:165], v[186:189], v[52:55]
	v_mfma_f32_16x16x32_bf16 v[44:47], v[144:147], v[194:197], v[44:47]
	v_mfma_f32_16x16x32_bf16 v[36:39], v[162:165], v[194:197], v[36:39]
	v_mfma_f32_16x16x32_bf16 v[28:31], v[144:147], v[202:205], v[28:31]
	v_mfma_f32_16x16x32_bf16 v[20:23], v[162:165], v[202:205], v[20:23]
	v_mfma_f32_16x16x32_bf16 v[12:15], v[144:147], v[218:221], v[12:15]
	v_mfma_f32_16x16x32_bf16 v[4:7], v[162:165], v[218:221], v[4:7]
	v_mfma_f32_16x16x32_bf16 v[60:63], v[148:151], v[190:193], v[60:63]
	v_mfma_f32_16x16x32_bf16 v[52:55], v[166:169], v[190:193], v[52:55]
	v_mfma_f32_16x16x32_bf16 v[44:47], v[148:151], v[198:201], v[44:47]
	v_mfma_f32_16x16x32_bf16 v[36:39], v[166:169], v[198:201], v[36:39]
	v_mfma_f32_16x16x32_bf16 v[28:31], v[148:151], v[214:217], v[28:31]
	v_mfma_f32_16x16x32_bf16 v[20:23], v[166:169], v[214:217], v[20:23]
	v_mfma_f32_16x16x32_bf16 v[12:15], v[148:151], v[222:225], v[12:15]
	v_mfma_f32_16x16x32_bf16 v[4:7], v[166:169], v[222:225], v[4:7]
	s_setprio 0
	s_setprio 1
	v_mfma_f32_16x16x32_bf16 v[56:59], v[170:173], v[186:189], v[56:59]
	v_mfma_f32_16x16x32_bf16 v[48:51], v[178:181], v[186:189], v[48:51]
	v_mfma_f32_16x16x32_bf16 v[40:43], v[170:173], v[194:197], v[40:43]
	v_mfma_f32_16x16x32_bf16 v[32:35], v[178:181], v[194:197], v[32:35]
	v_mfma_f32_16x16x32_bf16 v[24:27], v[170:173], v[202:205], v[24:27]
	v_mfma_f32_16x16x32_bf16 v[16:19], v[178:181], v[202:205], v[16:19]
	v_mfma_f32_16x16x32_bf16 v[8:11], v[170:173], v[218:221], v[8:11]
	v_mfma_f32_16x16x32_bf16 v[0:3], v[178:181], v[218:221], v[0:3]
	v_mfma_f32_16x16x32_bf16 v[56:59], v[174:177], v[190:193], v[56:59]
	v_mfma_f32_16x16x32_bf16 v[48:51], v[182:185], v[190:193], v[48:51]
	v_mfma_f32_16x16x32_bf16 v[40:43], v[174:177], v[198:201], v[40:43]
	v_mfma_f32_16x16x32_bf16 v[32:35], v[182:185], v[198:201], v[32:35]
	v_mfma_f32_16x16x32_bf16 v[24:27], v[174:177], v[214:217], v[24:27]
	v_mfma_f32_16x16x32_bf16 v[16:19], v[182:185], v[214:217], v[16:19]
	v_mfma_f32_16x16x32_bf16 v[8:11], v[174:177], v[222:225], v[8:11]
	v_mfma_f32_16x16x32_bf16 v[0:3], v[182:185], v[222:225], v[0:3]
	s_setprio 0
	s_barrier
	s_add_i32 s35, s35, 2
	s_add_u32 s33, s33, 0x100
	s_addc_u32 s34, s34, 0
	s_add_u32 s14, s14, 0x100
	s_addc_u32 s15, s15, 0
	s_cmp_gt_u32 s35, 29
	s_cbranch_scc0 .LBB0_1510
	s_and_b64 vcc, exec, s[4:5]
	s_cbranch_vccz .LBB0_1513
	s_barrier

.LBB0_1589:
	s_add_u32 s30, s12, 0x100
	v_mov_b32_e32 v0, 0
	s_addc_u32 s31, s13, 0
	s_mov_b32 s33, -2
	v_mov_b32_e32 v1, v0
	v_mov_b32_e32 v2, v0
	v_mov_b32_e32 v3, v0
	v_mov_b32_e32 v4, v0
	v_mov_b32_e32 v5, v0
	v_mov_b32_e32 v6, v0
	v_mov_b32_e32 v7, v0
	v_mov_b32_e32 v16, v0
	v_mov_b32_e32 v17, v0
	v_mov_b32_e32 v18, v0
	v_mov_b32_e32 v19, v0
	v_mov_b32_e32 v20, v0
	v_mov_b32_e32 v21, v0
	v_mov_b32_e32 v22, v0
	v_mov_b32_e32 v23, v0
	v_mov_b32_e32 v32, v0
	v_mov_b32_e32 v33, v0
	v_mov_b32_e32 v34, v0
	v_mov_b32_e32 v35, v0
	v_mov_b32_e32 v36, v0
	v_mov_b32_e32 v37, v0
	v_mov_b32_e32 v38, v0
	v_mov_b32_e32 v39, v0
	v_mov_b32_e32 v48, v0
	v_mov_b32_e32 v49, v0
	v_mov_b32_e32 v50, v0
	v_mov_b32_e32 v51, v0
	v_mov_b32_e32 v52, v0
	v_mov_b32_e32 v53, v0
	v_mov_b32_e32 v54, v0
	v_mov_b32_e32 v55, v0
	v_mov_b32_e32 v8, v0
	v_mov_b32_e32 v9, v0
	v_mov_b32_e32 v10, v0
	v_mov_b32_e32 v11, v0
	v_mov_b32_e32 v12, v0
	v_mov_b32_e32 v13, v0
	v_mov_b32_e32 v14, v0
	v_mov_b32_e32 v15, v0
	v_mov_b32_e32 v24, v0
	v_mov_b32_e32 v25, v0
	v_mov_b32_e32 v26, v0
	v_mov_b32_e32 v27, v0
	v_mov_b32_e32 v28, v0
	v_mov_b32_e32 v29, v0
	v_mov_b32_e32 v30, v0
	v_mov_b32_e32 v31, v0
	v_mov_b32_e32 v40, v0
	v_mov_b32_e32 v41, v0
	v_mov_b32_e32 v42, v0
	v_mov_b32_e32 v43, v0
	v_mov_b32_e32 v44, v0
	v_mov_b32_e32 v45, v0
	v_mov_b32_e32 v46, v0
	v_mov_b32_e32 v47, v0
	v_mov_b32_e32 v56, v0
	v_mov_b32_e32 v57, v0
	v_mov_b32_e32 v58, v0
	v_mov_b32_e32 v59, v0
	v_mov_b32_e32 v60, v0
	v_mov_b32_e32 v61, v0
	v_mov_b32_e32 v62, v0
	v_mov_b32_e32 v63, v0
	v_mov_b32_e32 v64, v0
	v_mov_b32_e32 v65, v0
	v_mov_b32_e32 v66, v0
	v_mov_b32_e32 v67, v0
	v_mov_b32_e32 v68, v0
	v_mov_b32_e32 v69, v0
	v_mov_b32_e32 v70, v0
	v_mov_b32_e32 v71, v0
	v_mov_b32_e32 v80, v0
	v_mov_b32_e32 v81, v0
	v_mov_b32_e32 v82, v0
	v_mov_b32_e32 v83, v0
	v_mov_b32_e32 v84, v0
	v_mov_b32_e32 v85, v0
	v_mov_b32_e32 v86, v0
	v_mov_b32_e32 v87, v0
	v_mov_b32_e32 v96, v0
	v_mov_b32_e32 v97, v0
	v_mov_b32_e32 v98, v0
	v_mov_b32_e32 v99, v0
	v_mov_b32_e32 v100, v0
	v_mov_b32_e32 v101, v0
	v_mov_b32_e32 v102, v0
	v_mov_b32_e32 v103, v0
	v_mov_b32_e32 v112, v0
	v_mov_b32_e32 v113, v0
	v_mov_b32_e32 v114, v0
	v_mov_b32_e32 v115, v0
	v_mov_b32_e32 v116, v0
	v_mov_b32_e32 v117, v0
	v_mov_b32_e32 v118, v0
	v_mov_b32_e32 v119, v0
	v_mov_b32_e32 v72, v0
	v_mov_b32_e32 v73, v0
	v_mov_b32_e32 v74, v0
	v_mov_b32_e32 v75, v0
	v_mov_b32_e32 v76, v0
	v_mov_b32_e32 v77, v0
	v_mov_b32_e32 v78, v0
	v_mov_b32_e32 v79, v0
	v_mov_b32_e32 v88, v0
	v_mov_b32_e32 v89, v0
	v_mov_b32_e32 v90, v0
	v_mov_b32_e32 v91, v0
	v_mov_b32_e32 v92, v0
	v_mov_b32_e32 v93, v0
	v_mov_b32_e32 v94, v0
	v_mov_b32_e32 v95, v0
	v_mov_b32_e32 v104, v0
	v_mov_b32_e32 v105, v0
	v_mov_b32_e32 v106, v0
	v_mov_b32_e32 v107, v0
	v_mov_b32_e32 v108, v0
	v_mov_b32_e32 v109, v0
	v_mov_b32_e32 v110, v0
	v_mov_b32_e32 v111, v0
	v_mov_b32_e32 v120, v0
	v_mov_b32_e32 v121, v0
	v_mov_b32_e32 v122, v0
	v_mov_b32_e32 v123, v0
	v_mov_b32_e32 v124, v0
	v_mov_b32_e32 v125, v0
	v_mov_b32_e32 v126, v0
	v_mov_b32_e32 v127, v0
	s_mov_b64 s[36:37], 0x80
	s_waitcnt vmcnt(0)
	v_add_u32_e32 v234, 0x10000, v141
	v_add_u32_e32 v235, 0x14000, v141
	v_add_u32_e32 v236, 0x18000, v141
	v_add_u32_e32 v237, 0x1c000, v141
.LBB0_1590:
	s_add_u32 s12, s10, 0x100
	s_addc_u32 s13, s11, 0
	s_add_i32 s34, 0, 0x10000
	s_cmpk_eq_i32 s33, 0x54
	s_cselect_b32 s17, s3, s13
	s_cselect_b32 s16, s2, s12
	s_cselect_b32 s15, s9, s31
	s_cselect_b32 s14, s8, s30
	s_add_i32 s35, 0, 0x14000
	ds_read_b128 v[134:137], v234
	ds_read_b128 v[144:147], v234 offset:1024
	ds_read_b128 v[148:151], v234 offset:2048
	ds_read_b128 v[162:165], v234 offset:3072
	ds_read_b128 v[166:169], v235
	ds_read_b128 v[170:173], v235 offset:1024
	ds_read_b128 v[174:177], v235 offset:2048
	ds_read_b128 v[178:181], v235 offset:3072
	s_add_i32 m0, s19, 0xc000
	ds_read_b128 v[182:185], v143
	ds_read_b128 v[186:189], v143 offset:1024
	ds_read_b128 v[190:193], v143 offset:2048
	ds_read_b128 v[194:197], v143 offset:3072
	ds_read_b128 v[198:201], v143 offset:4096
	ds_read_b128 v[202:205], v143 offset:5120
	ds_read_b128 v[214:217], v143 offset:6144
	ds_read_b128 v[218:221], v143 offset:7168
	global_load_lds_dwordx4 v132, s[10:11]
	s_add_i32 m0, s19, 0xe000
	s_nop 0
	global_load_lds_dwordx4 v130, s[10:11]
	s_waitcnt vmcnt(8)
	s_waitcnt lgkmcnt(0)
	s_barrier
	s_setprio 1
	s_waitcnt lgkmcnt(0)
	v_mfma_f32_16x16x32_bf16 v[124:127], v[134:137], v[182:185], v[124:127]
	v_mfma_f32_16x16x32_bf16 v[120:123], v[148:151], v[182:185], v[120:123]
	v_mfma_f32_16x16x32_bf16 v[108:111], v[134:137], v[190:193], v[108:111]
	v_mfma_f32_16x16x32_bf16 v[104:107], v[148:151], v[190:193], v[104:107]
	v_mfma_f32_16x16x32_bf16 v[92:95], v[134:137], v[198:201], v[92:95]
	v_mfma_f32_16x16x32_bf16 v[88:91], v[148:151], v[198:201], v[88:91]
	v_mfma_f32_16x16x32_bf16 v[76:79], v[134:137], v[214:217], v[76:79]
	v_mfma_f32_16x16x32_bf16 v[72:75], v[148:151], v[214:217], v[72:75]
	v_mfma_f32_16x16x32_bf16 v[124:127], v[144:147], v[186:189], v[124:127]
	v_mfma_f32_16x16x32_bf16 v[120:123], v[162:165], v[186:189], v[120:123]
	v_mfma_f32_16x16x32_bf16 v[108:111], v[144:147], v[194:197], v[108:111]
	v_mfma_f32_16x16x32_bf16 v[104:107], v[162:165], v[194:197], v[104:107]
	v_mfma_f32_16x16x32_bf16 v[92:95], v[144:147], v[202:205], v[92:95]
	v_mfma_f32_16x16x32_bf16 v[88:91], v[162:165], v[202:205], v[88:91]
	v_mfma_f32_16x16x32_bf16 v[76:79], v[144:147], v[218:221], v[76:79]
	v_mfma_f32_16x16x32_bf16 v[72:75], v[162:165], v[218:221], v[72:75]
	s_setprio 0
	s_setprio 1
	v_mfma_f32_16x16x32_bf16 v[116:119], v[166:169], v[182:185], v[116:119]
	v_mfma_f32_16x16x32_bf16 v[112:115], v[174:177], v[182:185], v[112:115]
	v_mfma_f32_16x16x32_bf16 v[100:103], v[166:169], v[190:193], v[100:103]
	v_mfma_f32_16x16x32_bf16 v[96:99], v[174:177], v[190:193], v[96:99]
	v_mfma_f32_16x16x32_bf16 v[84:87], v[166:169], v[198:201], v[84:87]
	v_mfma_f32_16x16x32_bf16 v[80:83], v[174:177], v[198:201], v[80:83]
	v_mfma_f32_16x16x32_bf16 v[68:71], v[166:169], v[214:217], v[68:71]
	v_mfma_f32_16x16x32_bf16 v[64:67], v[174:177], v[214:217], v[64:67]
	v_mfma_f32_16x16x32_bf16 v[116:119], v[170:173], v[186:189], v[116:119]
	v_mfma_f32_16x16x32_bf16 v[112:115], v[178:181], v[186:189], v[112:115]
	v_mfma_f32_16x16x32_bf16 v[100:103], v[170:173], v[194:197], v[100:103]
	v_mfma_f32_16x16x32_bf16 v[96:99], v[178:181], v[194:197], v[96:99]
	v_mfma_f32_16x16x32_bf16 v[84:87], v[170:173], v[202:205], v[84:87]
	v_mfma_f32_16x16x32_bf16 v[80:83], v[178:181], v[202:205], v[80:83]
	v_mfma_f32_16x16x32_bf16 v[68:71], v[170:173], v[218:221], v[68:71]
	v_mfma_f32_16x16x32_bf16 v[64:67], v[178:181], v[218:221], v[64:67]
	s_setprio 0
	s_barrier
	s_add_i32 s10, s34, s18
	s_add_u32 s100, s14, 0x80
	s_addc_u32 s101, s15, 0
	s_mov_b32 m0, s10
	ds_read_b128 v[182:185], v143 offset:16384
	ds_read_b128 v[186:189], v143 offset:17408
	ds_read_b128 v[190:193], v143 offset:18432
	ds_read_b128 v[194:197], v143 offset:19456
	ds_read_b128 v[198:201], v143 offset:20480
	ds_read_b128 v[202:205], v143 offset:21504
	ds_read_b128 v[214:217], v143 offset:22528
	ds_read_b128 v[218:221], v143 offset:23552
	global_load_lds_dwordx4 v152, s[14:15]
	s_add_i32 m0, s10, 0x2000
	s_add_u32 s10, s14, 0x160000
	s_addc_u32 s11, s15, 0
	s_add_i32 s34, s35, s18
	global_load_lds_dwordx4 v128, s[14:15]
	s_mov_b32 m0, s34
	s_nop 0
	global_load_lds_dwordx4 v152, s[10:11]
	s_add_i32 m0, s34, 0x2000
	s_nop 0
	global_load_lds_dwordx4 v128, s[10:11]
	s_add_u32 s98, s16, 0x80
	s_addc_u32 s99, s17, 0
	s_mov_b32 m0, s19
	s_nop 0
	global_load_lds_dwordx4 v152, s[16:17]
	s_mov_b32 m0, s20
	s_nop 0
	global_load_lds_dwordx4 v128, s[16:17]
	s_waitcnt vmcnt(8)
	s_waitcnt lgkmcnt(0)
	s_barrier
	s_setprio 1
	s_waitcnt lgkmcnt(0)
	v_mfma_f32_16x16x32_bf16 v[60:63], v[134:137], v[182:185], v[60:63]
	v_mfma_f32_16x16x32_bf16 v[56:59], v[148:151], v[182:185], v[56:59]
	v_mfma_f32_16x16x32_bf16 v[44:47], v[134:137], v[190:193], v[44:47]
	v_mfma_f32_16x16x32_bf16 v[40:43], v[148:151], v[190:193], v[40:43]
	v_mfma_f32_16x16x32_bf16 v[28:31], v[134:137], v[198:201], v[28:31]
	v_mfma_f32_16x16x32_bf16 v[24:27], v[148:151], v[198:201], v[24:27]
	v_mfma_f32_16x16x32_bf16 v[12:15], v[134:137], v[214:217], v[12:15]
	v_mfma_f32_16x16x32_bf16 v[8:11], v[148:151], v[214:217], v[8:11]
	v_mfma_f32_16x16x32_bf16 v[60:63], v[144:147], v[186:189], v[60:63]
	v_mfma_f32_16x16x32_bf16 v[56:59], v[162:165], v[186:189], v[56:59]
	v_mfma_f32_16x16x32_bf16 v[44:47], v[144:147], v[194:197], v[44:47]
	v_mfma_f32_16x16x32_bf16 v[40:43], v[162:165], v[194:197], v[40:43]
	v_mfma_f32_16x16x32_bf16 v[28:31], v[144:147], v[202:205], v[28:31]
	v_mfma_f32_16x16x32_bf16 v[24:27], v[162:165], v[202:205], v[24:27]
	v_mfma_f32_16x16x32_bf16 v[12:15], v[144:147], v[218:221], v[12:15]
	v_mfma_f32_16x16x32_bf16 v[8:11], v[162:165], v[218:221], v[8:11]
	s_setprio 0
	s_setprio 1
	v_mfma_f32_16x16x32_bf16 v[52:55], v[166:169], v[182:185], v[52:55]
	v_mfma_f32_16x16x32_bf16 v[48:51], v[174:177], v[182:185], v[48:51]
	v_mfma_f32_16x16x32_bf16 v[36:39], v[166:169], v[190:193], v[36:39]
	v_mfma_f32_16x16x32_bf16 v[32:35], v[174:177], v[190:193], v[32:35]
	v_mfma_f32_16x16x32_bf16 v[20:23], v[166:169], v[198:201], v[20:23]
	v_mfma_f32_16x16x32_bf16 v[16:19], v[174:177], v[198:201], v[16:19]
	v_mfma_f32_16x16x32_bf16 v[4:7], v[166:169], v[214:217], v[4:7]
	v_mfma_f32_16x16x32_bf16 v[0:3], v[174:177], v[214:217], v[0:3]
	v_mfma_f32_16x16x32_bf16 v[52:55], v[170:173], v[186:189], v[52:55]
	v_mfma_f32_16x16x32_bf16 v[48:51], v[178:181], v[186:189], v[48:51]
	v_mfma_f32_16x16x32_bf16 v[36:39], v[170:173], v[194:197], v[36:39]
	v_mfma_f32_16x16x32_bf16 v[32:35], v[178:181], v[194:197], v[32:35]
	v_mfma_f32_16x16x32_bf16 v[20:23], v[170:173], v[202:205], v[20:23]
	v_mfma_f32_16x16x32_bf16 v[16:19], v[178:181], v[202:205], v[16:19]
	v_mfma_f32_16x16x32_bf16 v[4:7], v[170:173], v[218:221], v[4:7]
	v_mfma_f32_16x16x32_bf16 v[0:3], v[178:181], v[218:221], v[0:3]
	s_setprio 0
	s_barrier
	s_add_i32 s34, 0, 0x18000
	s_add_i32 s35, 0, 0x1c000
	ds_read_b128 v[134:137], v236
	ds_read_b128 v[144:147], v236 offset:1024
	ds_read_b128 v[148:151], v236 offset:2048
	ds_read_b128 v[162:165], v236 offset:3072
	ds_read_b128 v[166:169], v237
	ds_read_b128 v[170:173], v237 offset:1024
	ds_read_b128 v[174:177], v237 offset:2048
	ds_read_b128 v[178:181], v237 offset:3072
	s_add_u32 s10, s16, 0x160000
	s_addc_u32 s11, s17, 0
	s_mov_b32 m0, s21
	ds_read_b128 v[182:185], v143 offset:32768
	ds_read_b128 v[186:189], v143 offset:33792
	ds_read_b128 v[190:193], v143 offset:34816
	ds_read_b128 v[194:197], v143 offset:35840
	ds_read_b128 v[198:201], v143 offset:36864
	ds_read_b128 v[202:205], v143 offset:37888
	ds_read_b128 v[214:217], v143 offset:38912
	ds_read_b128 v[218:221], v143 offset:39936
	global_load_lds_dwordx4 v152, s[10:11]
	s_mov_b32 m0, s22
	s_nop 0
	global_load_lds_dwordx4 v128, s[10:11]
	s_waitcnt vmcnt(8)
	s_waitcnt lgkmcnt(0)
	s_barrier
	s_setprio 1
	s_waitcnt lgkmcnt(0)
	v_mfma_f32_16x16x32_bf16 v[124:127], v[134:137], v[182:185], v[124:127]
	v_mfma_f32_16x16x32_bf16 v[120:123], v[148:151], v[182:185], v[120:123]
	v_mfma_f32_16x16x32_bf16 v[108:111], v[134:137], v[190:193], v[108:111]
	v_mfma_f32_16x16x32_bf16 v[104:107], v[148:151], v[190:193], v[104:107]
	v_mfma_f32_16x16x32_bf16 v[92:95], v[134:137], v[198:201], v[92:95]
	v_mfma_f32_16x16x32_bf16 v[88:91], v[148:151], v[198:201], v[88:91]
	v_mfma_f32_16x16x32_bf16 v[76:79], v[134:137], v[214:217], v[76:79]
	v_mfma_f32_16x16x32_bf16 v[72:75], v[148:151], v[214:217], v[72:75]
	v_mfma_f32_16x16x32_bf16 v[124:127], v[144:147], v[186:189], v[124:127]
	v_mfma_f32_16x16x32_bf16 v[120:123], v[162:165], v[186:189], v[120:123]
	v_mfma_f32_16x16x32_bf16 v[108:111], v[144:147], v[194:197], v[108:111]
	v_mfma_f32_16x16x32_bf16 v[104:107], v[162:165], v[194:197], v[104:107]
	v_mfma_f32_16x16x32_bf16 v[92:95], v[144:147], v[202:205], v[92:95]
	v_mfma_f32_16x16x32_bf16 v[88:91], v[162:165], v[202:205], v[88:91]
	v_mfma_f32_16x16x32_bf16 v[76:79], v[144:147], v[218:221], v[76:79]
	v_mfma_f32_16x16x32_bf16 v[72:75], v[162:165], v[218:221], v[72:75]
	s_setprio 0
	s_setprio 1
	v_mfma_f32_16x16x32_bf16 v[116:119], v[166:169], v[182:185], v[116:119]
	v_mfma_f32_16x16x32_bf16 v[112:115], v[174:177], v[182:185], v[112:115]
	v_mfma_f32_16x16x32_bf16 v[100:103], v[166:169], v[190:193], v[100:103]
	v_mfma_f32_16x16x32_bf16 v[96:99], v[174:177], v[190:193], v[96:99]
	v_mfma_f32_16x16x32_bf16 v[84:87], v[166:169], v[198:201], v[84:87]
	v_mfma_f32_16x16x32_bf16 v[80:83], v[174:177], v[198:201], v[80:83]
	v_mfma_f32_16x16x32_bf16 v[68:71], v[166:169], v[214:217], v[68:71]
	v_mfma_f32_16x16x32_bf16 v[64:67], v[174:177], v[214:217], v[64:67]
	v_mfma_f32_16x16x32_bf16 v[116:119], v[170:173], v[186:189], v[116:119]
	v_mfma_f32_16x16x32_bf16 v[112:115], v[178:181], v[186:189], v[112:115]
	v_mfma_f32_16x16x32_bf16 v[100:103], v[170:173], v[194:197], v[100:103]
	v_mfma_f32_16x16x32_bf16 v[96:99], v[178:181], v[194:197], v[96:99]
	v_mfma_f32_16x16x32_bf16 v[84:87], v[170:173], v[202:205], v[84:87]
	v_mfma_f32_16x16x32_bf16 v[80:83], v[178:181], v[202:205], v[80:83]
	v_mfma_f32_16x16x32_bf16 v[68:71], v[170:173], v[218:221], v[68:71]
	v_mfma_f32_16x16x32_bf16 v[64:67], v[178:181], v[218:221], v[64:67]
	s_setprio 0
	s_barrier
	s_add_i32 s10, s34, s18
	s_mov_b32 m0, s10
	ds_read_b128 v[182:185], v143 offset:49152
	ds_read_b128 v[186:189], v143 offset:50176
	ds_read_b128 v[190:193], v143 offset:51200
	ds_read_b128 v[194:197], v143 offset:52224
	ds_read_b128 v[198:201], v143 offset:53248
	ds_read_b128 v[202:205], v143 offset:54272
	ds_read_b128 v[214:217], v143 offset:55296
	ds_read_b128 v[218:221], v143 offset:56320
	global_load_lds_dwordx4 v152, s[100:101]
	s_add_i32 m0, s10, 0x2000
	s_add_u32 s10, s14, 0x160080
	s_addc_u32 s11, s15, 0
	s_add_i32 s14, s35, s18
	global_load_lds_dwordx4 v128, s[100:101]
	s_mov_b32 m0, s14
	s_nop 0
	global_load_lds_dwordx4 v152, s[10:11]
	s_add_i32 m0, s14, 0x2000
	s_nop 0
	global_load_lds_dwordx4 v128, s[10:11]
	s_mov_b32 m0, s23
	s_nop 0
	global_load_lds_dwordx4 v152, s[98:99]
	s_mov_b32 m0, s24
	s_nop 0
	global_load_lds_dwordx4 v128, s[98:99]
	s_waitcnt vmcnt(8)
	s_waitcnt lgkmcnt(0)
	s_barrier
	s_setprio 1
	s_waitcnt lgkmcnt(0)
	v_mfma_f32_16x16x32_bf16 v[60:63], v[134:137], v[182:185], v[60:63]
	v_mfma_f32_16x16x32_bf16 v[56:59], v[148:151], v[182:185], v[56:59]
	v_mfma_f32_16x16x32_bf16 v[44:47], v[134:137], v[190:193], v[44:47]
	v_mfma_f32_16x16x32_bf16 v[40:43], v[148:151], v[190:193], v[40:43]
	v_mfma_f32_16x16x32_bf16 v[28:31], v[134:137], v[198:201], v[28:31]
	v_mfma_f32_16x16x32_bf16 v[24:27], v[148:151], v[198:201], v[24:27]
	v_mfma_f32_16x16x32_bf16 v[12:15], v[134:137], v[214:217], v[12:15]
	v_mfma_f32_16x16x32_bf16 v[8:11], v[148:151], v[214:217], v[8:11]
	v_mfma_f32_16x16x32_bf16 v[60:63], v[144:147], v[186:189], v[60:63]
	v_mfma_f32_16x16x32_bf16 v[56:59], v[162:165], v[186:189], v[56:59]
	v_mfma_f32_16x16x32_bf16 v[44:47], v[144:147], v[194:197], v[44:47]
	v_mfma_f32_16x16x32_bf16 v[40:43], v[162:165], v[194:197], v[40:43]
	v_mfma_f32_16x16x32_bf16 v[28:31], v[144:147], v[202:205], v[28:31]
	v_mfma_f32_16x16x32_bf16 v[24:27], v[162:165], v[202:205], v[24:27]
	v_mfma_f32_16x16x32_bf16 v[12:15], v[144:147], v[218:221], v[12:15]
	v_mfma_f32_16x16x32_bf16 v[8:11], v[162:165], v[218:221], v[8:11]
	s_setprio 0
	s_setprio 1
	v_mfma_f32_16x16x32_bf16 v[52:55], v[166:169], v[182:185], v[52:55]
	v_mfma_f32_16x16x32_bf16 v[48:51], v[174:177], v[182:185], v[48:51]
	v_mfma_f32_16x16x32_bf16 v[36:39], v[166:169], v[190:193], v[36:39]
	v_mfma_f32_16x16x32_bf16 v[32:35], v[174:177], v[190:193], v[32:35]
	v_mfma_f32_16x16x32_bf16 v[20:23], v[166:169], v[198:201], v[20:23]
	v_mfma_f32_16x16x32_bf16 v[16:19], v[174:177], v[198:201], v[16:19]
	v_mfma_f32_16x16x32_bf16 v[4:7], v[166:169], v[214:217], v[4:7]
	v_mfma_f32_16x16x32_bf16 v[0:3], v[174:177], v[214:217], v[0:3]
	v_mfma_f32_16x16x32_bf16 v[52:55], v[170:173], v[186:189], v[52:55]
	v_mfma_f32_16x16x32_bf16 v[48:51], v[178:181], v[186:189], v[48:51]
	v_mfma_f32_16x16x32_bf16 v[36:39], v[170:173], v[194:197], v[36:39]
	v_mfma_f32_16x16x32_bf16 v[32:35], v[178:181], v[194:197], v[32:35]
	v_mfma_f32_16x16x32_bf16 v[20:23], v[170:173], v[202:205], v[20:23]
	v_mfma_f32_16x16x32_bf16 v[16:19], v[178:181], v[202:205], v[16:19]
	v_mfma_f32_16x16x32_bf16 v[4:7], v[170:173], v[218:221], v[4:7]
	v_mfma_f32_16x16x32_bf16 v[0:3], v[178:181], v[218:221], v[0:3]
	s_setprio 0
	s_barrier
	s_add_i32 s33, s33, 2
	s_add_u32 s30, s30, 0x100
	s_addc_u32 s31, s31, 0
	s_cmpk_gt_u32 s33, 0x55
	s_mov_b64 s[10:11], s[12:13]
	s_cbranch_scc0 .LBB0_1590
	s_and_b64 vcc, exec, s[6:7]
	s_cbranch_vccz .LBB0_1593
	s_barrier

	.amdhsa_kernel _Z9trunk_fwd4Args
		.amdhsa_group_segment_fixed_size 0
		.amdhsa_private_segment_fixed_size 0
		.amdhsa_kernarg_size 440
		.amdhsa_user_sgpr_count 2
		.amdhsa_user_sgpr_dispatch_ptr 0
		.amdhsa_user_sgpr_queue_ptr 0
		.amdhsa_user_sgpr_kernarg_segment_ptr 1
		.amdhsa_user_sgpr_dispatch_id 0
		.amdhsa_user_sgpr_kernarg_preload_length 0
		.amdhsa_user_sgpr_kernarg_preload_offset 0
		.amdhsa_user_sgpr_private_segment_size 0
		.amdhsa_uses_dynamic_stack 0
		.amdhsa_enable_private_segment 0
		.amdhsa_system_sgpr_workgroup_id_x 1
		.amdhsa_system_sgpr_workgroup_id_y 0
		.amdhsa_system_sgpr_workgroup_id_z 0
		.amdhsa_system_sgpr_workgroup_info 0
		.amdhsa_system_vgpr_workitem_id 0
		.amdhsa_next_free_vgpr 256
		.amdhsa_next_free_sgpr 102
		.amdhsa_accum_offset 256
		.amdhsa_reserve_vcc 1
		.amdhsa_float_round_mode_32 0
		.amdhsa_float_round_mode_16_64 0
		.amdhsa_float_denorm_mode_32 3
		.amdhsa_float_denorm_mode_16_64 3
		.amdhsa_dx10_clamp 1
		.amdhsa_ieee_mode 1
		.amdhsa_fp16_overflow 0
		.amdhsa_tg_split 0
		.amdhsa_exception_fp_ieee_invalid_op 0
		.amdhsa_exception_fp_denorm_src 0
		.amdhsa_exception_fp_ieee_div_zero 0
		.amdhsa_exception_fp_ieee_overflow 0
		.amdhsa_exception_fp_ieee_underflow 0
		.amdhsa_exception_fp_ieee_inexact 0
		.amdhsa_exception_int_div_zero 0
	.end_amdhsa_kernel

amdhsa.kernels:
  - .agpr_count:     0
    .args:
      - .offset:         0
        .size:           184
        .value_kind:     by_value
      - .offset:         184
        .size:           4
        .value_kind:     hidden_block_count_x
      - .offset:         188
        .size:           4
        .value_kind:     hidden_block_count_y
      - .offset:         192
        .size:           4
        .value_kind:     hidden_block_count_z
      - .offset:         196
        .size:           2
        .value_kind:     hidden_group_size_x
      - .offset:         198
        .size:           2
        .value_kind:     hidden_group_size_y
      - .offset:         200
        .size:           2
        .value_kind:     hidden_group_size_z
      - .offset:         202
        .size:           2
        .value_kind:     hidden_remainder_x
      - .offset:         204
        .size:           2
        .value_kind:     hidden_remainder_y
      - .offset:         206
        .size:           2
        .value_kind:     hidden_remainder_z
      - .offset:         224
        .size:           8
        .value_kind:     hidden_global_offset_x
      - .offset:         232
        .size:           8
        .value_kind:     hidden_global_offset_y
      - .offset:         240
        .size:           8
        .value_kind:     hidden_global_offset_z
      - .offset:         248
        .size:           2
        .value_kind:     hidden_grid_dims
      - .offset:         304
        .size:           4
        .value_kind:     hidden_dynamic_lds_size
    .group_segment_fixed_size: 0
    .kernarg_segment_align: 8
    .kernarg_segment_size: 440
    .language:       OpenCL C
    .language_version:
      - 2
      - 0
    .max_flat_workgroup_size: 512
    .name:           _Z9trunk_fwd4Args
    .private_segment_fixed_size: 0
    .sgpr_count:     108
    .sgpr_spill_count: 364
    .symbol:         _Z9trunk_fwd4Args.kd
    .uniform_work_group_size: 1
    .uses_dynamic_stack: false
    .vgpr_count:     256
    .vgpr_spill_count: 0
    .wavefront_size: 64
